# post0/post1 phases rewritten by hand: parameter vectors kept in registers (per-batch row mapping), next-iteration stream prefetch, DPP wave reductions
# speedup vs baseline: 1.0091x; 1.0091x over previous
.LBB0_308:
	s_setprio 0
	v_readlane_b32 s0, v255, 19
	v_readlane_b32 s1, v255, 20
	s_andn2_b64 vcc, exec, s[0:1]
	s_nop 0
	v_cndmask_b32_e64 v0, 0, 1, s[0:1]
	v_cmp_ne_u32_e64 s[8:9], 1, v0
	s_barrier
	v_mbcnt_lo_u32_b32 v0, -1, 0
	v_mbcnt_hi_u32_b32 v0, -1, v0
	s_cbranch_vccnz .LBB0_313
	s_cmp_lg_u32 s33, 0x100
	s_cbranch_scc1 .Lpost0_orig
	v_mbcnt_lo_u32_b32 v210, -1, 0
	v_mbcnt_hi_u32_b32 v210, -1, v210
	v_readlane_b32 s40, v255, 13
	v_readlane_b32 s41, v255, 14
	v_readlane_b32 s42, v255, 11
	v_readlane_b32 s43, v255, 12
	v_readlane_b32 s14, v255, 3
	v_readlane_b32 s15, v255, 4
	v_lshlrev_b32_e32 v211, 3, v210
	v_lshlrev_b32_e32 v210, 4, v210
	v_mov_b32_e32 v212, 0x358637bd
	s_lshr_b32 s1, s26, 9
	s_and_b32 s4, s26, 0x1ff
	s_lshl_b32 s5, s1, 13
	s_add_u32 s5, s5, s4
	s_mul_i32 s6, s1, 0x3000
	s_add_u32 s38, s34, s6
	s_addc_u32 s39, s35, 0
	s_add_u32 s44, s38, 0xc000
	s_addc_u32 s45, s39, 0
	s_add_u32 s46, s38, 0xd000
	s_addc_u32 s47, s39, 0
	s_add_u32 s42, s42, 0x1000
	s_addc_u32 s43, s43, 0
	s_add_u32 s38, s38, 0x2000
	s_addc_u32 s39, s39, 0
	s_mul_i32 s6, s5, 0x2000
	s_add_u32 s10, s62, s6
	s_addc_u32 s11, s63, 0
	s_add_u32 s12, s10, 0x400000
	s_addc_u32 s13, s11, 0
	s_lshl_b32 s6, s5, 12
	s_add_u32 s14, s14, s6
	s_addc_u32 s15, s15, 0
	s_add_u32 s16, s14, 0x200000
	s_addc_u32 s17, s15, 0
	s_add_u32 s18, s30, s6
	s_addc_u32 s19, s31, 0
	s_add_u32 s20, s18, 0x200000
	s_addc_u32 s21, s19, 0
	s_lshl_b32 s6, s5, 11
	s_add_u32 s24, s60, s6
	s_addc_u32 s25, s61, 0
	s_add_u32 s36, s24, 0x100000
	s_addc_u32 s37, s25, 0
	s_mov_b32 s4, 0
	global_load_dwordx4 v[96:99], v210, s[40:41]
	global_load_dwordx4 v[100:103], v210, s[40:41] offset:1024
	global_load_dwordx4 v[104:107], v210, s[40:41] offset:2048
	global_load_dwordx4 v[108:111], v210, s[40:41] offset:3072
	global_load_dwordx4 v[112:115], v210, s[38:39]
	global_load_dwordx4 v[116:119], v210, s[38:39] offset:1024
	global_load_dwordx4 v[120:123], v210, s[38:39] offset:2048
	global_load_dwordx4 v[124:127], v210, s[38:39] offset:3072
	global_load_dwordx4 v[128:131], v210, s[42:43]
	global_load_dwordx4 v[132:135], v210, s[42:43] offset:1024
	global_load_dwordx4 v[136:139], v210, s[42:43] offset:2048
	global_load_dwordx4 v[140:143], v210, s[42:43] offset:3072
	global_load_dwordx4 v[144:147], v210, s[44:45]
	global_load_dwordx4 v[148:151], v210, s[44:45] offset:1024
	global_load_dwordx4 v[152:155], v210, s[44:45] offset:2048
	global_load_dwordx4 v[156:159], v210, s[44:45] offset:3072
	global_load_dwordx4 v[160:163], v210, s[46:47]
	global_load_dwordx4 v[164:167], v210, s[46:47] offset:1024
	global_load_dwordx4 v[168:171], v210, s[46:47] offset:2048
	global_load_dwordx4 v[172:175], v210, s[46:47] offset:3072
	global_load_dwordx2 v[0:1], v211, s[10:11] nt
	global_load_dwordx2 v[2:3], v211, s[10:11] offset:512 nt
	global_load_dwordx2 v[4:5], v211, s[10:11] offset:1024 nt
	global_load_dwordx2 v[6:7], v211, s[10:11] offset:1536 nt
	global_load_dwordx4 v[16:19], v210, s[14:15] nt
	global_load_dwordx4 v[20:23], v210, s[14:15] offset:1024 nt
	global_load_dwordx4 v[24:27], v210, s[14:15] offset:2048 nt
	global_load_dwordx4 v[28:31], v210, s[14:15] offset:3072 nt
	global_load_dwordx2 v[8:9], v211, s[12:13] nt
	global_load_dwordx2 v[10:11], v211, s[12:13] offset:512 nt
	global_load_dwordx2 v[12:13], v211, s[12:13] offset:1024 nt
	global_load_dwordx2 v[14:15], v211, s[12:13] offset:1536 nt
	global_load_dwordx4 v[32:35], v210, s[16:17] nt
	global_load_dwordx4 v[36:39], v210, s[16:17] offset:1024 nt
	global_load_dwordx4 v[40:43], v210, s[16:17] offset:2048 nt
	global_load_dwordx4 v[44:47], v210, s[16:17] offset:3072 nt
	s_waitcnt vmcnt(0)
	v_add_f32_e32 v160, 1.0, v160
	v_add_f32_e32 v161, 1.0, v161
	v_add_f32_e32 v162, 1.0, v162
	v_add_f32_e32 v163, 1.0, v163
	v_add_f32_e32 v164, 1.0, v164
	v_add_f32_e32 v165, 1.0, v165
	v_add_f32_e32 v166, 1.0, v166
	v_add_f32_e32 v167, 1.0, v167
	v_add_f32_e32 v168, 1.0, v168
	v_add_f32_e32 v169, 1.0, v169
	v_add_f32_e32 v170, 1.0, v170
	v_add_f32_e32 v171, 1.0, v171
	v_add_f32_e32 v172, 1.0, v172
	v_add_f32_e32 v173, 1.0, v173
	v_add_f32_e32 v174, 1.0, v174
	v_add_f32_e32 v175, 1.0, v175
.Lpost0_loop:
	s_add_u32 s10, s10, 0x800000
	s_addc_u32 s11, s11, 0
	s_add_u32 s12, s12, 0x800000
	s_addc_u32 s13, s13, 0
	s_add_u32 s14, s14, 0x400000
	s_addc_u32 s15, s15, 0
	s_add_u32 s16, s16, 0x400000
	s_addc_u32 s17, s17, 0
	global_load_dwordx2 v[48:49], v211, s[10:11] nt
	global_load_dwordx2 v[50:51], v211, s[10:11] offset:512 nt
	global_load_dwordx2 v[52:53], v211, s[10:11] offset:1024 nt
	global_load_dwordx2 v[54:55], v211, s[10:11] offset:1536 nt
	global_load_dwordx4 v[64:67], v210, s[14:15] nt
	global_load_dwordx4 v[68:71], v210, s[14:15] offset:1024 nt
	global_load_dwordx4 v[72:75], v210, s[14:15] offset:2048 nt
	global_load_dwordx4 v[76:79], v210, s[14:15] offset:3072 nt
	global_load_dwordx2 v[56:57], v211, s[12:13] nt
	global_load_dwordx2 v[58:59], v211, s[12:13] offset:512 nt
	global_load_dwordx2 v[60:61], v211, s[12:13] offset:1024 nt
	global_load_dwordx2 v[62:63], v211, s[12:13] offset:1536 nt
	global_load_dwordx4 v[80:83], v210, s[16:17] nt
	global_load_dwordx4 v[84:87], v210, s[16:17] offset:1024 nt
	global_load_dwordx4 v[88:91], v210, s[16:17] offset:2048 nt
	global_load_dwordx4 v[92:95], v210, s[16:17] offset:3072 nt
	s_waitcnt vmcnt(40)
	v_lshlrev_b32_e32 v176, 16, v0
	v_and_b32_e32 v177, 0xffff0000, v0
	v_lshlrev_b32_e32 v178, 16, v1
	v_and_b32_e32 v179, 0xffff0000, v1
	v_lshlrev_b32_e32 v180, 16, v2
	v_and_b32_e32 v181, 0xffff0000, v2
	v_lshlrev_b32_e32 v182, 16, v3
	v_and_b32_e32 v183, 0xffff0000, v3
	v_lshlrev_b32_e32 v184, 16, v4
	v_and_b32_e32 v185, 0xffff0000, v4
	v_lshlrev_b32_e32 v186, 16, v5
	v_and_b32_e32 v187, 0xffff0000, v5
	v_lshlrev_b32_e32 v188, 16, v6
	v_and_b32_e32 v189, 0xffff0000, v6
	v_lshlrev_b32_e32 v190, 16, v7
	v_and_b32_e32 v191, 0xffff0000, v7
	v_mul_f32_e32 v192, v176, v176
	v_fmac_f32_e32 v192, v177, v177
	v_fmac_f32_e32 v192, v178, v178
	v_fmac_f32_e32 v192, v179, v179
	v_fmac_f32_e32 v192, v180, v180
	v_fmac_f32_e32 v192, v181, v181
	v_fmac_f32_e32 v192, v182, v182
	v_fmac_f32_e32 v192, v183, v183
	v_fmac_f32_e32 v192, v184, v184
	v_fmac_f32_e32 v192, v185, v185
	v_fmac_f32_e32 v192, v186, v186
	v_fmac_f32_e32 v192, v187, v187
	v_fmac_f32_e32 v192, v188, v188
	v_fmac_f32_e32 v192, v189, v189
	v_fmac_f32_e32 v192, v190, v190
	v_fmac_f32_e32 v192, v191, v191
	v_mul_f32_e32 v194, v112, v176
	v_mul_f32_e32 v195, v113, v177
	v_mul_f32_e32 v196, v114, v178
	v_mul_f32_e32 v197, v115, v179
	v_mul_f32_e32 v198, v116, v180
	v_mul_f32_e32 v199, v117, v181
	v_mul_f32_e32 v200, v118, v182
	v_mul_f32_e32 v201, v119, v183
	v_mul_f32_e32 v202, v120, v184
	v_mul_f32_e32 v203, v121, v185
	v_mul_f32_e32 v204, v122, v186
	v_mul_f32_e32 v205, v123, v187
	v_mul_f32_e32 v206, v124, v188
	v_mul_f32_e32 v207, v125, v189
	v_mul_f32_e32 v208, v126, v190
	v_mul_f32_e32 v209, v127, v191
	s_nop 1
	v_add_f32_dpp v193, v192, v192 quad_perm:[1,0,3,2] row_mask:0xf bank_mask:0xf
	s_nop 1
	v_add_f32_dpp v192, v193, v193 quad_perm:[2,3,0,1] row_mask:0xf bank_mask:0xf
	s_nop 1
	v_add_f32_dpp v193, v192, v192 row_half_mirror row_mask:0xf bank_mask:0xf
	s_nop 1
	v_add_f32_dpp v192, v193, v193 row_mirror row_mask:0xf bank_mask:0xf
	s_nop 0
	v_readlane_b32 s0, v192, 0
	v_readlane_b32 s1, v192, 16
	v_readlane_b32 s6, v192, 32
	v_readlane_b32 s7, v192, 48
	s_nop 1
	v_mov_b32_e32 v193, s0
	v_add_f32_e32 v193, s1, v193
	v_add_f32_e32 v193, s6, v193
	v_add_f32_e32 v193, s7, v193
	v_fmamk_f32 v193, v193, 0x3a800000, v212
	v_rsq_f32_e32 v213, v193
	s_nop 0
	v_mul_f32_e32 v194, v213, v194
	v_mul_f32_e32 v195, v213, v195
	v_mul_f32_e32 v196, v213, v196
	v_mul_f32_e32 v197, v213, v197
	v_mul_f32_e32 v198, v213, v198
	v_mul_f32_e32 v199, v213, v199
	v_mul_f32_e32 v200, v213, v200
	v_mul_f32_e32 v201, v213, v201
	v_mul_f32_e32 v202, v213, v202
	v_mul_f32_e32 v203, v213, v203
	v_mul_f32_e32 v204, v213, v204
	v_mul_f32_e32 v205, v213, v205
	v_mul_f32_e32 v206, v213, v206
	v_mul_f32_e32 v207, v213, v207
	v_mul_f32_e32 v208, v213, v208
	v_mul_f32_e32 v209, v213, v209
	v_fmac_f32_e32 v16, v96, v194
	v_fmac_f32_e32 v17, v97, v195
	v_fmac_f32_e32 v18, v98, v196
	v_fmac_f32_e32 v19, v99, v197
	v_fmac_f32_e32 v20, v100, v198
	v_fmac_f32_e32 v21, v101, v199
	v_fmac_f32_e32 v22, v102, v200
	v_fmac_f32_e32 v23, v103, v201
	v_fmac_f32_e32 v24, v104, v202
	v_fmac_f32_e32 v25, v105, v203
	v_fmac_f32_e32 v26, v106, v204
	v_fmac_f32_e32 v27, v107, v205
	v_fmac_f32_e32 v28, v108, v206
	v_fmac_f32_e32 v29, v109, v207
	v_fmac_f32_e32 v30, v110, v208
	v_fmac_f32_e32 v31, v111, v209
	global_store_dwordx4 v210, v[16:19], s[18:19] nt
	global_store_dwordx4 v210, v[20:23], s[18:19] offset:1024 nt
	global_store_dwordx4 v210, v[24:27], s[18:19] offset:2048 nt
	global_store_dwordx4 v210, v[28:31], s[18:19] offset:3072 nt
	v_mul_f32_e32 v192, v16, v16
	v_fmac_f32_e32 v192, v17, v17
	v_fmac_f32_e32 v192, v18, v18
	v_fmac_f32_e32 v192, v19, v19
	v_fmac_f32_e32 v192, v20, v20
	v_fmac_f32_e32 v192, v21, v21
	v_fmac_f32_e32 v192, v22, v22
	v_fmac_f32_e32 v192, v23, v23
	v_fmac_f32_e32 v192, v24, v24
	v_fmac_f32_e32 v192, v25, v25
	v_fmac_f32_e32 v192, v26, v26
	v_fmac_f32_e32 v192, v27, v27
	v_fmac_f32_e32 v192, v28, v28
	v_fmac_f32_e32 v192, v29, v29
	v_fmac_f32_e32 v192, v30, v30
	v_fmac_f32_e32 v192, v31, v31
	s_nop 1
	v_add_f32_dpp v193, v192, v192 quad_perm:[1,0,3,2] row_mask:0xf bank_mask:0xf
	s_nop 1
	v_add_f32_dpp v192, v193, v193 quad_perm:[2,3,0,1] row_mask:0xf bank_mask:0xf
	s_nop 1
	v_add_f32_dpp v193, v192, v192 row_half_mirror row_mask:0xf bank_mask:0xf
	s_nop 1
	v_add_f32_dpp v192, v193, v193 row_mirror row_mask:0xf bank_mask:0xf
	s_nop 0
	v_readlane_b32 s0, v192, 0
	v_readlane_b32 s1, v192, 16
	v_readlane_b32 s6, v192, 32
	v_readlane_b32 s7, v192, 48
	s_nop 1
	v_mov_b32_e32 v193, s0
	v_add_f32_e32 v193, s1, v193
	v_add_f32_e32 v193, s6, v193
	v_add_f32_e32 v193, s7, v193
	v_fmamk_f32 v193, v193, 0x3a800000, v212
	v_rsq_f32_e32 v213, v193
	s_nop 0
	v_mul_f32_e32 v194, v16, v213
	v_mul_f32_e32 v195, v17, v213
	v_mul_f32_e32 v196, v18, v213
	v_mul_f32_e32 v197, v19, v213
	v_mul_f32_e32 v198, v20, v213
	v_mul_f32_e32 v199, v21, v213
	v_mul_f32_e32 v200, v22, v213
	v_mul_f32_e32 v201, v23, v213
	v_mul_f32_e32 v202, v24, v213
	v_mul_f32_e32 v203, v25, v213
	v_mul_f32_e32 v204, v26, v213
	v_mul_f32_e32 v205, v27, v213
	v_mul_f32_e32 v206, v28, v213
	v_mul_f32_e32 v207, v29, v213
	v_mul_f32_e32 v208, v30, v213
	v_mul_f32_e32 v209, v31, v213
	v_mul_f32_e32 v194, v128, v194
	v_mul_f32_e32 v195, v129, v195
	v_mul_f32_e32 v196, v130, v196
	v_mul_f32_e32 v197, v131, v197
	v_mul_f32_e32 v198, v132, v198
	v_mul_f32_e32 v199, v133, v199
	v_mul_f32_e32 v200, v134, v200
	v_mul_f32_e32 v201, v135, v201
	v_mul_f32_e32 v202, v136, v202
	v_mul_f32_e32 v203, v137, v203
	v_mul_f32_e32 v204, v138, v204
	v_mul_f32_e32 v205, v139, v205
	v_mul_f32_e32 v206, v140, v206
	v_mul_f32_e32 v207, v141, v207
	v_mul_f32_e32 v208, v142, v208
	v_mul_f32_e32 v209, v143, v209
	v_fma_f32 v194, v194, v160, v144
	v_fma_f32 v195, v195, v161, v145
	v_fma_f32 v196, v196, v162, v146
	v_fma_f32 v197, v197, v163, v147
	v_fma_f32 v198, v198, v164, v148
	v_fma_f32 v199, v199, v165, v149
	v_fma_f32 v200, v200, v166, v150
	v_fma_f32 v201, v201, v167, v151
	v_fma_f32 v202, v202, v168, v152
	v_fma_f32 v203, v203, v169, v153
	v_fma_f32 v204, v204, v170, v154
	v_fma_f32 v205, v205, v171, v155
	v_fma_f32 v206, v206, v172, v156
	v_fma_f32 v207, v207, v173, v157
	v_fma_f32 v208, v208, v174, v158
	v_fma_f32 v209, v209, v175, v159
	v_cvt_pk_bf16_f32 v194, v194, v195
	v_cvt_pk_bf16_f32 v195, v196, v197
	v_cvt_pk_bf16_f32 v196, v198, v199
	v_cvt_pk_bf16_f32 v197, v200, v201
	v_cvt_pk_bf16_f32 v198, v202, v203
	v_cvt_pk_bf16_f32 v199, v204, v205
	v_cvt_pk_bf16_f32 v200, v206, v207
	v_cvt_pk_bf16_f32 v201, v208, v209
	global_store_dwordx2 v211, v[194:195], s[24:25] nt
	global_store_dwordx2 v211, v[196:197], s[24:25] offset:512 nt
	global_store_dwordx2 v211, v[198:199], s[24:25] offset:1024 nt
	global_store_dwordx2 v211, v[200:201], s[24:25] offset:1536 nt
	s_waitcnt vmcnt(24)
	v_lshlrev_b32_e32 v176, 16, v8
	v_and_b32_e32 v177, 0xffff0000, v8
	v_lshlrev_b32_e32 v178, 16, v9
	v_and_b32_e32 v179, 0xffff0000, v9
	v_lshlrev_b32_e32 v180, 16, v10
	v_and_b32_e32 v181, 0xffff0000, v10
	v_lshlrev_b32_e32 v182, 16, v11
	v_and_b32_e32 v183, 0xffff0000, v11
	v_lshlrev_b32_e32 v184, 16, v12
	v_and_b32_e32 v185, 0xffff0000, v12
	v_lshlrev_b32_e32 v186, 16, v13
	v_and_b32_e32 v187, 0xffff0000, v13
	v_lshlrev_b32_e32 v188, 16, v14
	v_and_b32_e32 v189, 0xffff0000, v14
	v_lshlrev_b32_e32 v190, 16, v15
	v_and_b32_e32 v191, 0xffff0000, v15
	v_mul_f32_e32 v192, v176, v176
	v_fmac_f32_e32 v192, v177, v177
	v_fmac_f32_e32 v192, v178, v178
	v_fmac_f32_e32 v192, v179, v179
	v_fmac_f32_e32 v192, v180, v180
	v_fmac_f32_e32 v192, v181, v181
	v_fmac_f32_e32 v192, v182, v182
	v_fmac_f32_e32 v192, v183, v183
	v_fmac_f32_e32 v192, v184, v184
	v_fmac_f32_e32 v192, v185, v185
	v_fmac_f32_e32 v192, v186, v186
	v_fmac_f32_e32 v192, v187, v187
	v_fmac_f32_e32 v192, v188, v188
	v_fmac_f32_e32 v192, v189, v189
	v_fmac_f32_e32 v192, v190, v190
	v_fmac_f32_e32 v192, v191, v191
	v_mul_f32_e32 v194, v112, v176
	v_mul_f32_e32 v195, v113, v177
	v_mul_f32_e32 v196, v114, v178
	v_mul_f32_e32 v197, v115, v179
	v_mul_f32_e32 v198, v116, v180
	v_mul_f32_e32 v199, v117, v181
	v_mul_f32_e32 v200, v118, v182
	v_mul_f32_e32 v201, v119, v183
	v_mul_f32_e32 v202, v120, v184
	v_mul_f32_e32 v203, v121, v185
	v_mul_f32_e32 v204, v122, v186
	v_mul_f32_e32 v205, v123, v187
	v_mul_f32_e32 v206, v124, v188
	v_mul_f32_e32 v207, v125, v189
	v_mul_f32_e32 v208, v126, v190
	v_mul_f32_e32 v209, v127, v191
	s_nop 1
	v_add_f32_dpp v193, v192, v192 quad_perm:[1,0,3,2] row_mask:0xf bank_mask:0xf
	s_nop 1
	v_add_f32_dpp v192, v193, v193 quad_perm:[2,3,0,1] row_mask:0xf bank_mask:0xf
	s_nop 1
	v_add_f32_dpp v193, v192, v192 row_half_mirror row_mask:0xf bank_mask:0xf
	s_nop 1
	v_add_f32_dpp v192, v193, v193 row_mirror row_mask:0xf bank_mask:0xf
	s_nop 0
	v_readlane_b32 s0, v192, 0
	v_readlane_b32 s1, v192, 16
	v_readlane_b32 s6, v192, 32
	v_readlane_b32 s7, v192, 48
	s_nop 1
	v_mov_b32_e32 v193, s0
	v_add_f32_e32 v193, s1, v193
	v_add_f32_e32 v193, s6, v193
	v_add_f32_e32 v193, s7, v193
	v_fmamk_f32 v193, v193, 0x3a800000, v212
	v_rsq_f32_e32 v213, v193
	s_nop 0
	v_mul_f32_e32 v194, v213, v194
	v_mul_f32_e32 v195, v213, v195
	v_mul_f32_e32 v196, v213, v196
	v_mul_f32_e32 v197, v213, v197
	v_mul_f32_e32 v198, v213, v198
	v_mul_f32_e32 v199, v213, v199
	v_mul_f32_e32 v200, v213, v200
	v_mul_f32_e32 v201, v213, v201
	v_mul_f32_e32 v202, v213, v202
	v_mul_f32_e32 v203, v213, v203
	v_mul_f32_e32 v204, v213, v204
	v_mul_f32_e32 v205, v213, v205
	v_mul_f32_e32 v206, v213, v206
	v_mul_f32_e32 v207, v213, v207
	v_mul_f32_e32 v208, v213, v208
	v_mul_f32_e32 v209, v213, v209
	v_fmac_f32_e32 v32, v96, v194
	v_fmac_f32_e32 v33, v97, v195
	v_fmac_f32_e32 v34, v98, v196
	v_fmac_f32_e32 v35, v99, v197
	v_fmac_f32_e32 v36, v100, v198
	v_fmac_f32_e32 v37, v101, v199
	v_fmac_f32_e32 v38, v102, v200
	v_fmac_f32_e32 v39, v103, v201
	v_fmac_f32_e32 v40, v104, v202
	v_fmac_f32_e32 v41, v105, v203
	v_fmac_f32_e32 v42, v106, v204
	v_fmac_f32_e32 v43, v107, v205
	v_fmac_f32_e32 v44, v108, v206
	v_fmac_f32_e32 v45, v109, v207
	v_fmac_f32_e32 v46, v110, v208
	v_fmac_f32_e32 v47, v111, v209
	global_store_dwordx4 v210, v[32:35], s[20:21] nt
	global_store_dwordx4 v210, v[36:39], s[20:21] offset:1024 nt
	global_store_dwordx4 v210, v[40:43], s[20:21] offset:2048 nt
	global_store_dwordx4 v210, v[44:47], s[20:21] offset:3072 nt
	v_mul_f32_e32 v192, v32, v32
	v_fmac_f32_e32 v192, v33, v33
	v_fmac_f32_e32 v192, v34, v34
	v_fmac_f32_e32 v192, v35, v35
	v_fmac_f32_e32 v192, v36, v36
	v_fmac_f32_e32 v192, v37, v37
	v_fmac_f32_e32 v192, v38, v38
	v_fmac_f32_e32 v192, v39, v39
	v_fmac_f32_e32 v192, v40, v40
	v_fmac_f32_e32 v192, v41, v41
	v_fmac_f32_e32 v192, v42, v42
	v_fmac_f32_e32 v192, v43, v43
	v_fmac_f32_e32 v192, v44, v44
	v_fmac_f32_e32 v192, v45, v45
	v_fmac_f32_e32 v192, v46, v46
	v_fmac_f32_e32 v192, v47, v47
	s_nop 1
	v_add_f32_dpp v193, v192, v192 quad_perm:[1,0,3,2] row_mask:0xf bank_mask:0xf
	s_nop 1
	v_add_f32_dpp v192, v193, v193 quad_perm:[2,3,0,1] row_mask:0xf bank_mask:0xf
	s_nop 1
	v_add_f32_dpp v193, v192, v192 row_half_mirror row_mask:0xf bank_mask:0xf
	s_nop 1
	v_add_f32_dpp v192, v193, v193 row_mirror row_mask:0xf bank_mask:0xf
	s_nop 0
	v_readlane_b32 s0, v192, 0
	v_readlane_b32 s1, v192, 16
	v_readlane_b32 s6, v192, 32
	v_readlane_b32 s7, v192, 48
	s_nop 1
	v_mov_b32_e32 v193, s0
	v_add_f32_e32 v193, s1, v193
	v_add_f32_e32 v193, s6, v193
	v_add_f32_e32 v193, s7, v193
	v_fmamk_f32 v193, v193, 0x3a800000, v212
	v_rsq_f32_e32 v213, v193
	s_nop 0
	v_mul_f32_e32 v194, v32, v213
	v_mul_f32_e32 v195, v33, v213
	v_mul_f32_e32 v196, v34, v213
	v_mul_f32_e32 v197, v35, v213
	v_mul_f32_e32 v198, v36, v213
	v_mul_f32_e32 v199, v37, v213
	v_mul_f32_e32 v200, v38, v213
	v_mul_f32_e32 v201, v39, v213
	v_mul_f32_e32 v202, v40, v213
	v_mul_f32_e32 v203, v41, v213
	v_mul_f32_e32 v204, v42, v213
	v_mul_f32_e32 v205, v43, v213
	v_mul_f32_e32 v206, v44, v213
	v_mul_f32_e32 v207, v45, v213
	v_mul_f32_e32 v208, v46, v213
	v_mul_f32_e32 v209, v47, v213
	v_mul_f32_e32 v194, v128, v194
	v_mul_f32_e32 v195, v129, v195
	v_mul_f32_e32 v196, v130, v196
	v_mul_f32_e32 v197, v131, v197
	v_mul_f32_e32 v198, v132, v198
	v_mul_f32_e32 v199, v133, v199
	v_mul_f32_e32 v200, v134, v200
	v_mul_f32_e32 v201, v135, v201
	v_mul_f32_e32 v202, v136, v202
	v_mul_f32_e32 v203, v137, v203
	v_mul_f32_e32 v204, v138, v204
	v_mul_f32_e32 v205, v139, v205
	v_mul_f32_e32 v206, v140, v206
	v_mul_f32_e32 v207, v141, v207
	v_mul_f32_e32 v208, v142, v208
	v_mul_f32_e32 v209, v143, v209
	v_fma_f32 v194, v194, v160, v144
	v_fma_f32 v195, v195, v161, v145
	v_fma_f32 v196, v196, v162, v146
	v_fma_f32 v197, v197, v163, v147
	v_fma_f32 v198, v198, v164, v148
	v_fma_f32 v199, v199, v165, v149
	v_fma_f32 v200, v200, v166, v150
	v_fma_f32 v201, v201, v167, v151
	v_fma_f32 v202, v202, v168, v152
	v_fma_f32 v203, v203, v169, v153
	v_fma_f32 v204, v204, v170, v154
	v_fma_f32 v205, v205, v171, v155
	v_fma_f32 v206, v206, v172, v156
	v_fma_f32 v207, v207, v173, v157
	v_fma_f32 v208, v208, v174, v158
	v_fma_f32 v209, v209, v175, v159
	v_cvt_pk_bf16_f32 v194, v194, v195
	v_cvt_pk_bf16_f32 v195, v196, v197
	v_cvt_pk_bf16_f32 v196, v198, v199
	v_cvt_pk_bf16_f32 v197, v200, v201
	v_cvt_pk_bf16_f32 v198, v202, v203
	v_cvt_pk_bf16_f32 v199, v204, v205
	v_cvt_pk_bf16_f32 v200, v206, v207
	v_cvt_pk_bf16_f32 v201, v208, v209
	global_store_dwordx2 v211, v[194:195], s[36:37] nt
	global_store_dwordx2 v211, v[196:197], s[36:37] offset:512 nt
	global_store_dwordx2 v211, v[198:199], s[36:37] offset:1024 nt
	global_store_dwordx2 v211, v[200:201], s[36:37] offset:1536 nt
	s_add_u32 s18, s18, 0x400000
	s_addc_u32 s19, s19, 0
	s_add_u32 s20, s20, 0x400000
	s_addc_u32 s21, s21, 0
	s_add_u32 s24, s24, 0x200000
	s_addc_u32 s25, s25, 0
	s_add_u32 s36, s36, 0x200000
	s_addc_u32 s37, s37, 0
	s_cmp_eq_u32 s4, 3
	s_cbranch_scc1 .Lpost0_last
	s_add_u32 s10, s10, 0x800000
	s_addc_u32 s11, s11, 0
	s_add_u32 s12, s12, 0x800000
	s_addc_u32 s13, s13, 0
	s_add_u32 s14, s14, 0x400000
	s_addc_u32 s15, s15, 0
	s_add_u32 s16, s16, 0x400000
	s_addc_u32 s17, s17, 0
	global_load_dwordx2 v[0:1], v211, s[10:11] nt
	global_load_dwordx2 v[2:3], v211, s[10:11] offset:512 nt
	global_load_dwordx2 v[4:5], v211, s[10:11] offset:1024 nt
	global_load_dwordx2 v[6:7], v211, s[10:11] offset:1536 nt
	global_load_dwordx4 v[16:19], v210, s[14:15] nt
	global_load_dwordx4 v[20:23], v210, s[14:15] offset:1024 nt
	global_load_dwordx4 v[24:27], v210, s[14:15] offset:2048 nt
	global_load_dwordx4 v[28:31], v210, s[14:15] offset:3072 nt
	global_load_dwordx2 v[8:9], v211, s[12:13] nt
	global_load_dwordx2 v[10:11], v211, s[12:13] offset:512 nt
	global_load_dwordx2 v[12:13], v211, s[12:13] offset:1024 nt
	global_load_dwordx2 v[14:15], v211, s[12:13] offset:1536 nt
	global_load_dwordx4 v[32:35], v210, s[16:17] nt
	global_load_dwordx4 v[36:39], v210, s[16:17] offset:1024 nt
	global_load_dwordx4 v[40:43], v210, s[16:17] offset:2048 nt
	global_load_dwordx4 v[44:47], v210, s[16:17] offset:3072 nt
	s_waitcnt vmcnt(40)
	v_lshlrev_b32_e32 v176, 16, v48
	v_and_b32_e32 v177, 0xffff0000, v48
	v_lshlrev_b32_e32 v178, 16, v49
	v_and_b32_e32 v179, 0xffff0000, v49
	v_lshlrev_b32_e32 v180, 16, v50
	v_and_b32_e32 v181, 0xffff0000, v50
	v_lshlrev_b32_e32 v182, 16, v51
	v_and_b32_e32 v183, 0xffff0000, v51
	v_lshlrev_b32_e32 v184, 16, v52
	v_and_b32_e32 v185, 0xffff0000, v52
	v_lshlrev_b32_e32 v186, 16, v53
	v_and_b32_e32 v187, 0xffff0000, v53
	v_lshlrev_b32_e32 v188, 16, v54
	v_and_b32_e32 v189, 0xffff0000, v54
	v_lshlrev_b32_e32 v190, 16, v55
	v_and_b32_e32 v191, 0xffff0000, v55
	v_mul_f32_e32 v192, v176, v176
	v_fmac_f32_e32 v192, v177, v177
	v_fmac_f32_e32 v192, v178, v178
	v_fmac_f32_e32 v192, v179, v179
	v_fmac_f32_e32 v192, v180, v180
	v_fmac_f32_e32 v192, v181, v181
	v_fmac_f32_e32 v192, v182, v182
	v_fmac_f32_e32 v192, v183, v183
	v_fmac_f32_e32 v192, v184, v184
	v_fmac_f32_e32 v192, v185, v185
	v_fmac_f32_e32 v192, v186, v186
	v_fmac_f32_e32 v192, v187, v187
	v_fmac_f32_e32 v192, v188, v188
	v_fmac_f32_e32 v192, v189, v189
	v_fmac_f32_e32 v192, v190, v190
	v_fmac_f32_e32 v192, v191, v191
	v_mul_f32_e32 v194, v112, v176
	v_mul_f32_e32 v195, v113, v177
	v_mul_f32_e32 v196, v114, v178
	v_mul_f32_e32 v197, v115, v179
	v_mul_f32_e32 v198, v116, v180
	v_mul_f32_e32 v199, v117, v181
	v_mul_f32_e32 v200, v118, v182
	v_mul_f32_e32 v201, v119, v183
	v_mul_f32_e32 v202, v120, v184
	v_mul_f32_e32 v203, v121, v185
	v_mul_f32_e32 v204, v122, v186
	v_mul_f32_e32 v205, v123, v187
	v_mul_f32_e32 v206, v124, v188
	v_mul_f32_e32 v207, v125, v189
	v_mul_f32_e32 v208, v126, v190
	v_mul_f32_e32 v209, v127, v191
	s_nop 1
	v_add_f32_dpp v193, v192, v192 quad_perm:[1,0,3,2] row_mask:0xf bank_mask:0xf
	s_nop 1
	v_add_f32_dpp v192, v193, v193 quad_perm:[2,3,0,1] row_mask:0xf bank_mask:0xf
	s_nop 1
	v_add_f32_dpp v193, v192, v192 row_half_mirror row_mask:0xf bank_mask:0xf
	s_nop 1
	v_add_f32_dpp v192, v193, v193 row_mirror row_mask:0xf bank_mask:0xf
	s_nop 0
	v_readlane_b32 s0, v192, 0
	v_readlane_b32 s1, v192, 16
	v_readlane_b32 s6, v192, 32
	v_readlane_b32 s7, v192, 48
	s_nop 1
	v_mov_b32_e32 v193, s0
	v_add_f32_e32 v193, s1, v193
	v_add_f32_e32 v193, s6, v193
	v_add_f32_e32 v193, s7, v193
	v_fmamk_f32 v193, v193, 0x3a800000, v212
	v_rsq_f32_e32 v213, v193
	s_nop 0
	v_mul_f32_e32 v194, v213, v194
	v_mul_f32_e32 v195, v213, v195
	v_mul_f32_e32 v196, v213, v196
	v_mul_f32_e32 v197, v213, v197
	v_mul_f32_e32 v198, v213, v198
	v_mul_f32_e32 v199, v213, v199
	v_mul_f32_e32 v200, v213, v200
	v_mul_f32_e32 v201, v213, v201
	v_mul_f32_e32 v202, v213, v202
	v_mul_f32_e32 v203, v213, v203
	v_mul_f32_e32 v204, v213, v204
	v_mul_f32_e32 v205, v213, v205
	v_mul_f32_e32 v206, v213, v206
	v_mul_f32_e32 v207, v213, v207
	v_mul_f32_e32 v208, v213, v208
	v_mul_f32_e32 v209, v213, v209
	v_fmac_f32_e32 v64, v96, v194
	v_fmac_f32_e32 v65, v97, v195
	v_fmac_f32_e32 v66, v98, v196
	v_fmac_f32_e32 v67, v99, v197
	v_fmac_f32_e32 v68, v100, v198
	v_fmac_f32_e32 v69, v101, v199
	v_fmac_f32_e32 v70, v102, v200
	v_fmac_f32_e32 v71, v103, v201
	v_fmac_f32_e32 v72, v104, v202
	v_fmac_f32_e32 v73, v105, v203
	v_fmac_f32_e32 v74, v106, v204
	v_fmac_f32_e32 v75, v107, v205
	v_fmac_f32_e32 v76, v108, v206
	v_fmac_f32_e32 v77, v109, v207
	v_fmac_f32_e32 v78, v110, v208
	v_fmac_f32_e32 v79, v111, v209
	global_store_dwordx4 v210, v[64:67], s[18:19] nt
	global_store_dwordx4 v210, v[68:71], s[18:19] offset:1024 nt
	global_store_dwordx4 v210, v[72:75], s[18:19] offset:2048 nt
	global_store_dwordx4 v210, v[76:79], s[18:19] offset:3072 nt
	v_mul_f32_e32 v192, v64, v64
	v_fmac_f32_e32 v192, v65, v65
	v_fmac_f32_e32 v192, v66, v66
	v_fmac_f32_e32 v192, v67, v67
	v_fmac_f32_e32 v192, v68, v68
	v_fmac_f32_e32 v192, v69, v69
	v_fmac_f32_e32 v192, v70, v70
	v_fmac_f32_e32 v192, v71, v71
	v_fmac_f32_e32 v192, v72, v72
	v_fmac_f32_e32 v192, v73, v73
	v_fmac_f32_e32 v192, v74, v74
	v_fmac_f32_e32 v192, v75, v75
	v_fmac_f32_e32 v192, v76, v76
	v_fmac_f32_e32 v192, v77, v77
	v_fmac_f32_e32 v192, v78, v78
	v_fmac_f32_e32 v192, v79, v79
	s_nop 1
	v_add_f32_dpp v193, v192, v192 quad_perm:[1,0,3,2] row_mask:0xf bank_mask:0xf
	s_nop 1
	v_add_f32_dpp v192, v193, v193 quad_perm:[2,3,0,1] row_mask:0xf bank_mask:0xf
	s_nop 1
	v_add_f32_dpp v193, v192, v192 row_half_mirror row_mask:0xf bank_mask:0xf
	s_nop 1
	v_add_f32_dpp v192, v193, v193 row_mirror row_mask:0xf bank_mask:0xf
	s_nop 0
	v_readlane_b32 s0, v192, 0
	v_readlane_b32 s1, v192, 16
	v_readlane_b32 s6, v192, 32
	v_readlane_b32 s7, v192, 48
	s_nop 1
	v_mov_b32_e32 v193, s0
	v_add_f32_e32 v193, s1, v193
	v_add_f32_e32 v193, s6, v193
	v_add_f32_e32 v193, s7, v193
	v_fmamk_f32 v193, v193, 0x3a800000, v212
	v_rsq_f32_e32 v213, v193
	s_nop 0
	v_mul_f32_e32 v194, v64, v213
	v_mul_f32_e32 v195, v65, v213
	v_mul_f32_e32 v196, v66, v213
	v_mul_f32_e32 v197, v67, v213
	v_mul_f32_e32 v198, v68, v213
	v_mul_f32_e32 v199, v69, v213
	v_mul_f32_e32 v200, v70, v213
	v_mul_f32_e32 v201, v71, v213
	v_mul_f32_e32 v202, v72, v213
	v_mul_f32_e32 v203, v73, v213
	v_mul_f32_e32 v204, v74, v213
	v_mul_f32_e32 v205, v75, v213
	v_mul_f32_e32 v206, v76, v213
	v_mul_f32_e32 v207, v77, v213
	v_mul_f32_e32 v208, v78, v213
	v_mul_f32_e32 v209, v79, v213
	v_mul_f32_e32 v194, v128, v194
	v_mul_f32_e32 v195, v129, v195
	v_mul_f32_e32 v196, v130, v196
	v_mul_f32_e32 v197, v131, v197
	v_mul_f32_e32 v198, v132, v198
	v_mul_f32_e32 v199, v133, v199
	v_mul_f32_e32 v200, v134, v200
	v_mul_f32_e32 v201, v135, v201
	v_mul_f32_e32 v202, v136, v202
	v_mul_f32_e32 v203, v137, v203
	v_mul_f32_e32 v204, v138, v204
	v_mul_f32_e32 v205, v139, v205
	v_mul_f32_e32 v206, v140, v206
	v_mul_f32_e32 v207, v141, v207
	v_mul_f32_e32 v208, v142, v208
	v_mul_f32_e32 v209, v143, v209
	v_fma_f32 v194, v194, v160, v144
	v_fma_f32 v195, v195, v161, v145
	v_fma_f32 v196, v196, v162, v146
	v_fma_f32 v197, v197, v163, v147
	v_fma_f32 v198, v198, v164, v148
	v_fma_f32 v199, v199, v165, v149
	v_fma_f32 v200, v200, v166, v150
	v_fma_f32 v201, v201, v167, v151
	v_fma_f32 v202, v202, v168, v152
	v_fma_f32 v203, v203, v169, v153
	v_fma_f32 v204, v204, v170, v154
	v_fma_f32 v205, v205, v171, v155
	v_fma_f32 v206, v206, v172, v156
	v_fma_f32 v207, v207, v173, v157
	v_fma_f32 v208, v208, v174, v158
	v_fma_f32 v209, v209, v175, v159
	v_cvt_pk_bf16_f32 v194, v194, v195
	v_cvt_pk_bf16_f32 v195, v196, v197
	v_cvt_pk_bf16_f32 v196, v198, v199
	v_cvt_pk_bf16_f32 v197, v200, v201
	v_cvt_pk_bf16_f32 v198, v202, v203
	v_cvt_pk_bf16_f32 v199, v204, v205
	v_cvt_pk_bf16_f32 v200, v206, v207
	v_cvt_pk_bf16_f32 v201, v208, v209
	global_store_dwordx2 v211, v[194:195], s[24:25] nt
	global_store_dwordx2 v211, v[196:197], s[24:25] offset:512 nt
	global_store_dwordx2 v211, v[198:199], s[24:25] offset:1024 nt
	global_store_dwordx2 v211, v[200:201], s[24:25] offset:1536 nt
	s_waitcnt vmcnt(24)
	v_lshlrev_b32_e32 v176, 16, v56
	v_and_b32_e32 v177, 0xffff0000, v56
	v_lshlrev_b32_e32 v178, 16, v57
	v_and_b32_e32 v179, 0xffff0000, v57
	v_lshlrev_b32_e32 v180, 16, v58
	v_and_b32_e32 v181, 0xffff0000, v58
	v_lshlrev_b32_e32 v182, 16, v59
	v_and_b32_e32 v183, 0xffff0000, v59
	v_lshlrev_b32_e32 v184, 16, v60
	v_and_b32_e32 v185, 0xffff0000, v60
	v_lshlrev_b32_e32 v186, 16, v61
	v_and_b32_e32 v187, 0xffff0000, v61
	v_lshlrev_b32_e32 v188, 16, v62
	v_and_b32_e32 v189, 0xffff0000, v62
	v_lshlrev_b32_e32 v190, 16, v63
	v_and_b32_e32 v191, 0xffff0000, v63
	v_mul_f32_e32 v192, v176, v176
	v_fmac_f32_e32 v192, v177, v177
	v_fmac_f32_e32 v192, v178, v178
	v_fmac_f32_e32 v192, v179, v179
	v_fmac_f32_e32 v192, v180, v180
	v_fmac_f32_e32 v192, v181, v181
	v_fmac_f32_e32 v192, v182, v182
	v_fmac_f32_e32 v192, v183, v183
	v_fmac_f32_e32 v192, v184, v184
	v_fmac_f32_e32 v192, v185, v185
	v_fmac_f32_e32 v192, v186, v186
	v_fmac_f32_e32 v192, v187, v187
	v_fmac_f32_e32 v192, v188, v188
	v_fmac_f32_e32 v192, v189, v189
	v_fmac_f32_e32 v192, v190, v190
	v_fmac_f32_e32 v192, v191, v191
	v_mul_f32_e32 v194, v112, v176
	v_mul_f32_e32 v195, v113, v177
	v_mul_f32_e32 v196, v114, v178
	v_mul_f32_e32 v197, v115, v179
	v_mul_f32_e32 v198, v116, v180
	v_mul_f32_e32 v199, v117, v181
	v_mul_f32_e32 v200, v118, v182
	v_mul_f32_e32 v201, v119, v183
	v_mul_f32_e32 v202, v120, v184
	v_mul_f32_e32 v203, v121, v185
	v_mul_f32_e32 v204, v122, v186
	v_mul_f32_e32 v205, v123, v187
	v_mul_f32_e32 v206, v124, v188
	v_mul_f32_e32 v207, v125, v189
	v_mul_f32_e32 v208, v126, v190
	v_mul_f32_e32 v209, v127, v191
	s_nop 1
	v_add_f32_dpp v193, v192, v192 quad_perm:[1,0,3,2] row_mask:0xf bank_mask:0xf
	s_nop 1
	v_add_f32_dpp v192, v193, v193 quad_perm:[2,3,0,1] row_mask:0xf bank_mask:0xf
	s_nop 1
	v_add_f32_dpp v193, v192, v192 row_half_mirror row_mask:0xf bank_mask:0xf
	s_nop 1
	v_add_f32_dpp v192, v193, v193 row_mirror row_mask:0xf bank_mask:0xf
	s_nop 0
	v_readlane_b32 s0, v192, 0
	v_readlane_b32 s1, v192, 16
	v_readlane_b32 s6, v192, 32
	v_readlane_b32 s7, v192, 48
	s_nop 1
	v_mov_b32_e32 v193, s0
	v_add_f32_e32 v193, s1, v193
	v_add_f32_e32 v193, s6, v193
	v_add_f32_e32 v193, s7, v193
	v_fmamk_f32 v193, v193, 0x3a800000, v212
	v_rsq_f32_e32 v213, v193
	s_nop 0
	v_mul_f32_e32 v194, v213, v194
	v_mul_f32_e32 v195, v213, v195
	v_mul_f32_e32 v196, v213, v196
	v_mul_f32_e32 v197, v213, v197
	v_mul_f32_e32 v198, v213, v198
	v_mul_f32_e32 v199, v213, v199
	v_mul_f32_e32 v200, v213, v200
	v_mul_f32_e32 v201, v213, v201
	v_mul_f32_e32 v202, v213, v202
	v_mul_f32_e32 v203, v213, v203
	v_mul_f32_e32 v204, v213, v204
	v_mul_f32_e32 v205, v213, v205
	v_mul_f32_e32 v206, v213, v206
	v_mul_f32_e32 v207, v213, v207
	v_mul_f32_e32 v208, v213, v208
	v_mul_f32_e32 v209, v213, v209
	v_fmac_f32_e32 v80, v96, v194
	v_fmac_f32_e32 v81, v97, v195
	v_fmac_f32_e32 v82, v98, v196
	v_fmac_f32_e32 v83, v99, v197
	v_fmac_f32_e32 v84, v100, v198
	v_fmac_f32_e32 v85, v101, v199
	v_fmac_f32_e32 v86, v102, v200
	v_fmac_f32_e32 v87, v103, v201
	v_fmac_f32_e32 v88, v104, v202
	v_fmac_f32_e32 v89, v105, v203
	v_fmac_f32_e32 v90, v106, v204
	v_fmac_f32_e32 v91, v107, v205
	v_fmac_f32_e32 v92, v108, v206
	v_fmac_f32_e32 v93, v109, v207
	v_fmac_f32_e32 v94, v110, v208
	v_fmac_f32_e32 v95, v111, v209
	global_store_dwordx4 v210, v[80:83], s[20:21] nt
	global_store_dwordx4 v210, v[84:87], s[20:21] offset:1024 nt
	global_store_dwordx4 v210, v[88:91], s[20:21] offset:2048 nt
	global_store_dwordx4 v210, v[92:95], s[20:21] offset:3072 nt
	v_mul_f32_e32 v192, v80, v80
	v_fmac_f32_e32 v192, v81, v81
	v_fmac_f32_e32 v192, v82, v82
	v_fmac_f32_e32 v192, v83, v83
	v_fmac_f32_e32 v192, v84, v84
	v_fmac_f32_e32 v192, v85, v85
	v_fmac_f32_e32 v192, v86, v86
	v_fmac_f32_e32 v192, v87, v87
	v_fmac_f32_e32 v192, v88, v88
	v_fmac_f32_e32 v192, v89, v89
	v_fmac_f32_e32 v192, v90, v90
	v_fmac_f32_e32 v192, v91, v91
	v_fmac_f32_e32 v192, v92, v92
	v_fmac_f32_e32 v192, v93, v93
	v_fmac_f32_e32 v192, v94, v94
	v_fmac_f32_e32 v192, v95, v95
	s_nop 1
	v_add_f32_dpp v193, v192, v192 quad_perm:[1,0,3,2] row_mask:0xf bank_mask:0xf
	s_nop 1
	v_add_f32_dpp v192, v193, v193 quad_perm:[2,3,0,1] row_mask:0xf bank_mask:0xf
	s_nop 1
	v_add_f32_dpp v193, v192, v192 row_half_mirror row_mask:0xf bank_mask:0xf
	s_nop 1
	v_add_f32_dpp v192, v193, v193 row_mirror row_mask:0xf bank_mask:0xf
	s_nop 0
	v_readlane_b32 s0, v192, 0
	v_readlane_b32 s1, v192, 16
	v_readlane_b32 s6, v192, 32
	v_readlane_b32 s7, v192, 48
	s_nop 1
	v_mov_b32_e32 v193, s0
	v_add_f32_e32 v193, s1, v193
	v_add_f32_e32 v193, s6, v193
	v_add_f32_e32 v193, s7, v193
	v_fmamk_f32 v193, v193, 0x3a800000, v212
	v_rsq_f32_e32 v213, v193
	s_nop 0
	v_mul_f32_e32 v194, v80, v213
	v_mul_f32_e32 v195, v81, v213
	v_mul_f32_e32 v196, v82, v213
	v_mul_f32_e32 v197, v83, v213
	v_mul_f32_e32 v198, v84, v213
	v_mul_f32_e32 v199, v85, v213
	v_mul_f32_e32 v200, v86, v213
	v_mul_f32_e32 v201, v87, v213
	v_mul_f32_e32 v202, v88, v213
	v_mul_f32_e32 v203, v89, v213
	v_mul_f32_e32 v204, v90, v213
	v_mul_f32_e32 v205, v91, v213
	v_mul_f32_e32 v206, v92, v213
	v_mul_f32_e32 v207, v93, v213
	v_mul_f32_e32 v208, v94, v213
	v_mul_f32_e32 v209, v95, v213
	v_mul_f32_e32 v194, v128, v194
	v_mul_f32_e32 v195, v129, v195
	v_mul_f32_e32 v196, v130, v196
	v_mul_f32_e32 v197, v131, v197
	v_mul_f32_e32 v198, v132, v198
	v_mul_f32_e32 v199, v133, v199
	v_mul_f32_e32 v200, v134, v200
	v_mul_f32_e32 v201, v135, v201
	v_mul_f32_e32 v202, v136, v202
	v_mul_f32_e32 v203, v137, v203
	v_mul_f32_e32 v204, v138, v204
	v_mul_f32_e32 v205, v139, v205
	v_mul_f32_e32 v206, v140, v206
	v_mul_f32_e32 v207, v141, v207
	v_mul_f32_e32 v208, v142, v208
	v_mul_f32_e32 v209, v143, v209
	v_fma_f32 v194, v194, v160, v144
	v_fma_f32 v195, v195, v161, v145
	v_fma_f32 v196, v196, v162, v146
	v_fma_f32 v197, v197, v163, v147
	v_fma_f32 v198, v198, v164, v148
	v_fma_f32 v199, v199, v165, v149
	v_fma_f32 v200, v200, v166, v150
	v_fma_f32 v201, v201, v167, v151
	v_fma_f32 v202, v202, v168, v152
	v_fma_f32 v203, v203, v169, v153
	v_fma_f32 v204, v204, v170, v154
	v_fma_f32 v205, v205, v171, v155
	v_fma_f32 v206, v206, v172, v156
	v_fma_f32 v207, v207, v173, v157
	v_fma_f32 v208, v208, v174, v158
	v_fma_f32 v209, v209, v175, v159
	v_cvt_pk_bf16_f32 v194, v194, v195
	v_cvt_pk_bf16_f32 v195, v196, v197
	v_cvt_pk_bf16_f32 v196, v198, v199
	v_cvt_pk_bf16_f32 v197, v200, v201
	v_cvt_pk_bf16_f32 v198, v202, v203
	v_cvt_pk_bf16_f32 v199, v204, v205
	v_cvt_pk_bf16_f32 v200, v206, v207
	v_cvt_pk_bf16_f32 v201, v208, v209
	global_store_dwordx2 v211, v[194:195], s[36:37] nt
	global_store_dwordx2 v211, v[196:197], s[36:37] offset:512 nt
	global_store_dwordx2 v211, v[198:199], s[36:37] offset:1024 nt
	global_store_dwordx2 v211, v[200:201], s[36:37] offset:1536 nt
	s_add_u32 s18, s18, 0x400000
	s_addc_u32 s19, s19, 0
	s_add_u32 s20, s20, 0x400000
	s_addc_u32 s21, s21, 0
	s_add_u32 s24, s24, 0x200000
	s_addc_u32 s25, s25, 0
	s_add_u32 s36, s36, 0x200000
	s_addc_u32 s37, s37, 0
	s_add_u32 s4, s4, 1
	s_branch .Lpost0_loop
.Lpost0_last:
	s_waitcnt vmcnt(24)
	v_lshlrev_b32_e32 v176, 16, v48
	v_and_b32_e32 v177, 0xffff0000, v48
	v_lshlrev_b32_e32 v178, 16, v49
	v_and_b32_e32 v179, 0xffff0000, v49
	v_lshlrev_b32_e32 v180, 16, v50
	v_and_b32_e32 v181, 0xffff0000, v50
	v_lshlrev_b32_e32 v182, 16, v51
	v_and_b32_e32 v183, 0xffff0000, v51
	v_lshlrev_b32_e32 v184, 16, v52
	v_and_b32_e32 v185, 0xffff0000, v52
	v_lshlrev_b32_e32 v186, 16, v53
	v_and_b32_e32 v187, 0xffff0000, v53
	v_lshlrev_b32_e32 v188, 16, v54
	v_and_b32_e32 v189, 0xffff0000, v54
	v_lshlrev_b32_e32 v190, 16, v55
	v_and_b32_e32 v191, 0xffff0000, v55
	v_mul_f32_e32 v192, v176, v176
	v_fmac_f32_e32 v192, v177, v177
	v_fmac_f32_e32 v192, v178, v178
	v_fmac_f32_e32 v192, v179, v179
	v_fmac_f32_e32 v192, v180, v180
	v_fmac_f32_e32 v192, v181, v181
	v_fmac_f32_e32 v192, v182, v182
	v_fmac_f32_e32 v192, v183, v183
	v_fmac_f32_e32 v192, v184, v184
	v_fmac_f32_e32 v192, v185, v185
	v_fmac_f32_e32 v192, v186, v186
	v_fmac_f32_e32 v192, v187, v187
	v_fmac_f32_e32 v192, v188, v188
	v_fmac_f32_e32 v192, v189, v189
	v_fmac_f32_e32 v192, v190, v190
	v_fmac_f32_e32 v192, v191, v191
	v_mul_f32_e32 v194, v112, v176
	v_mul_f32_e32 v195, v113, v177
	v_mul_f32_e32 v196, v114, v178
	v_mul_f32_e32 v197, v115, v179
	v_mul_f32_e32 v198, v116, v180
	v_mul_f32_e32 v199, v117, v181
	v_mul_f32_e32 v200, v118, v182
	v_mul_f32_e32 v201, v119, v183
	v_mul_f32_e32 v202, v120, v184
	v_mul_f32_e32 v203, v121, v185
	v_mul_f32_e32 v204, v122, v186
	v_mul_f32_e32 v205, v123, v187
	v_mul_f32_e32 v206, v124, v188
	v_mul_f32_e32 v207, v125, v189
	v_mul_f32_e32 v208, v126, v190
	v_mul_f32_e32 v209, v127, v191
	s_nop 1
	v_add_f32_dpp v193, v192, v192 quad_perm:[1,0,3,2] row_mask:0xf bank_mask:0xf
	s_nop 1
	v_add_f32_dpp v192, v193, v193 quad_perm:[2,3,0,1] row_mask:0xf bank_mask:0xf
	s_nop 1
	v_add_f32_dpp v193, v192, v192 row_half_mirror row_mask:0xf bank_mask:0xf
	s_nop 1
	v_add_f32_dpp v192, v193, v193 row_mirror row_mask:0xf bank_mask:0xf
	s_nop 0
	v_readlane_b32 s0, v192, 0
	v_readlane_b32 s1, v192, 16
	v_readlane_b32 s6, v192, 32
	v_readlane_b32 s7, v192, 48
	s_nop 1
	v_mov_b32_e32 v193, s0
	v_add_f32_e32 v193, s1, v193
	v_add_f32_e32 v193, s6, v193
	v_add_f32_e32 v193, s7, v193
	v_fmamk_f32 v193, v193, 0x3a800000, v212
	v_rsq_f32_e32 v213, v193
	s_nop 0
	v_mul_f32_e32 v194, v213, v194
	v_mul_f32_e32 v195, v213, v195
	v_mul_f32_e32 v196, v213, v196
	v_mul_f32_e32 v197, v213, v197
	v_mul_f32_e32 v198, v213, v198
	v_mul_f32_e32 v199, v213, v199
	v_mul_f32_e32 v200, v213, v200
	v_mul_f32_e32 v201, v213, v201
	v_mul_f32_e32 v202, v213, v202
	v_mul_f32_e32 v203, v213, v203
	v_mul_f32_e32 v204, v213, v204
	v_mul_f32_e32 v205, v213, v205
	v_mul_f32_e32 v206, v213, v206
	v_mul_f32_e32 v207, v213, v207
	v_mul_f32_e32 v208, v213, v208
	v_mul_f32_e32 v209, v213, v209
	v_fmac_f32_e32 v64, v96, v194
	v_fmac_f32_e32 v65, v97, v195
	v_fmac_f32_e32 v66, v98, v196
	v_fmac_f32_e32 v67, v99, v197
	v_fmac_f32_e32 v68, v100, v198
	v_fmac_f32_e32 v69, v101, v199
	v_fmac_f32_e32 v70, v102, v200
	v_fmac_f32_e32 v71, v103, v201
	v_fmac_f32_e32 v72, v104, v202
	v_fmac_f32_e32 v73, v105, v203
	v_fmac_f32_e32 v74, v106, v204
	v_fmac_f32_e32 v75, v107, v205
	v_fmac_f32_e32 v76, v108, v206
	v_fmac_f32_e32 v77, v109, v207
	v_fmac_f32_e32 v78, v110, v208
	v_fmac_f32_e32 v79, v111, v209
	global_store_dwordx4 v210, v[64:67], s[18:19] nt
	global_store_dwordx4 v210, v[68:71], s[18:19] offset:1024 nt
	global_store_dwordx4 v210, v[72:75], s[18:19] offset:2048 nt
	global_store_dwordx4 v210, v[76:79], s[18:19] offset:3072 nt
	v_mul_f32_e32 v192, v64, v64
	v_fmac_f32_e32 v192, v65, v65
	v_fmac_f32_e32 v192, v66, v66
	v_fmac_f32_e32 v192, v67, v67
	v_fmac_f32_e32 v192, v68, v68
	v_fmac_f32_e32 v192, v69, v69
	v_fmac_f32_e32 v192, v70, v70
	v_fmac_f32_e32 v192, v71, v71
	v_fmac_f32_e32 v192, v72, v72
	v_fmac_f32_e32 v192, v73, v73
	v_fmac_f32_e32 v192, v74, v74
	v_fmac_f32_e32 v192, v75, v75
	v_fmac_f32_e32 v192, v76, v76
	v_fmac_f32_e32 v192, v77, v77
	v_fmac_f32_e32 v192, v78, v78
	v_fmac_f32_e32 v192, v79, v79
	s_nop 1
	v_add_f32_dpp v193, v192, v192 quad_perm:[1,0,3,2] row_mask:0xf bank_mask:0xf
	s_nop 1
	v_add_f32_dpp v192, v193, v193 quad_perm:[2,3,0,1] row_mask:0xf bank_mask:0xf
	s_nop 1
	v_add_f32_dpp v193, v192, v192 row_half_mirror row_mask:0xf bank_mask:0xf
	s_nop 1
	v_add_f32_dpp v192, v193, v193 row_mirror row_mask:0xf bank_mask:0xf
	s_nop 0
	v_readlane_b32 s0, v192, 0
	v_readlane_b32 s1, v192, 16
	v_readlane_b32 s6, v192, 32
	v_readlane_b32 s7, v192, 48
	s_nop 1
	v_mov_b32_e32 v193, s0
	v_add_f32_e32 v193, s1, v193
	v_add_f32_e32 v193, s6, v193
	v_add_f32_e32 v193, s7, v193
	v_fmamk_f32 v193, v193, 0x3a800000, v212
	v_rsq_f32_e32 v213, v193
	s_nop 0
	v_mul_f32_e32 v194, v64, v213
	v_mul_f32_e32 v195, v65, v213
	v_mul_f32_e32 v196, v66, v213
	v_mul_f32_e32 v197, v67, v213
	v_mul_f32_e32 v198, v68, v213
	v_mul_f32_e32 v199, v69, v213
	v_mul_f32_e32 v200, v70, v213
	v_mul_f32_e32 v201, v71, v213
	v_mul_f32_e32 v202, v72, v213
	v_mul_f32_e32 v203, v73, v213
	v_mul_f32_e32 v204, v74, v213
	v_mul_f32_e32 v205, v75, v213
	v_mul_f32_e32 v206, v76, v213
	v_mul_f32_e32 v207, v77, v213
	v_mul_f32_e32 v208, v78, v213
	v_mul_f32_e32 v209, v79, v213
	v_mul_f32_e32 v194, v128, v194
	v_mul_f32_e32 v195, v129, v195
	v_mul_f32_e32 v196, v130, v196
	v_mul_f32_e32 v197, v131, v197
	v_mul_f32_e32 v198, v132, v198
	v_mul_f32_e32 v199, v133, v199
	v_mul_f32_e32 v200, v134, v200
	v_mul_f32_e32 v201, v135, v201
	v_mul_f32_e32 v202, v136, v202
	v_mul_f32_e32 v203, v137, v203
	v_mul_f32_e32 v204, v138, v204
	v_mul_f32_e32 v205, v139, v205
	v_mul_f32_e32 v206, v140, v206
	v_mul_f32_e32 v207, v141, v207
	v_mul_f32_e32 v208, v142, v208
	v_mul_f32_e32 v209, v143, v209
	v_fma_f32 v194, v194, v160, v144
	v_fma_f32 v195, v195, v161, v145
	v_fma_f32 v196, v196, v162, v146
	v_fma_f32 v197, v197, v163, v147
	v_fma_f32 v198, v198, v164, v148
	v_fma_f32 v199, v199, v165, v149
	v_fma_f32 v200, v200, v166, v150
	v_fma_f32 v201, v201, v167, v151
	v_fma_f32 v202, v202, v168, v152
	v_fma_f32 v203, v203, v169, v153
	v_fma_f32 v204, v204, v170, v154
	v_fma_f32 v205, v205, v171, v155
	v_fma_f32 v206, v206, v172, v156
	v_fma_f32 v207, v207, v173, v157
	v_fma_f32 v208, v208, v174, v158
	v_fma_f32 v209, v209, v175, v159
	v_cvt_pk_bf16_f32 v194, v194, v195
	v_cvt_pk_bf16_f32 v195, v196, v197
	v_cvt_pk_bf16_f32 v196, v198, v199
	v_cvt_pk_bf16_f32 v197, v200, v201
	v_cvt_pk_bf16_f32 v198, v202, v203
	v_cvt_pk_bf16_f32 v199, v204, v205
	v_cvt_pk_bf16_f32 v200, v206, v207
	v_cvt_pk_bf16_f32 v201, v208, v209
	global_store_dwordx2 v211, v[194:195], s[24:25] nt
	global_store_dwordx2 v211, v[196:197], s[24:25] offset:512 nt
	global_store_dwordx2 v211, v[198:199], s[24:25] offset:1024 nt
	global_store_dwordx2 v211, v[200:201], s[24:25] offset:1536 nt
	s_waitcnt vmcnt(8)
	v_lshlrev_b32_e32 v176, 16, v56
	v_and_b32_e32 v177, 0xffff0000, v56
	v_lshlrev_b32_e32 v178, 16, v57
	v_and_b32_e32 v179, 0xffff0000, v57
	v_lshlrev_b32_e32 v180, 16, v58
	v_and_b32_e32 v181, 0xffff0000, v58
	v_lshlrev_b32_e32 v182, 16, v59
	v_and_b32_e32 v183, 0xffff0000, v59
	v_lshlrev_b32_e32 v184, 16, v60
	v_and_b32_e32 v185, 0xffff0000, v60
	v_lshlrev_b32_e32 v186, 16, v61
	v_and_b32_e32 v187, 0xffff0000, v61
	v_lshlrev_b32_e32 v188, 16, v62
	v_and_b32_e32 v189, 0xffff0000, v62
	v_lshlrev_b32_e32 v190, 16, v63
	v_and_b32_e32 v191, 0xffff0000, v63
	v_mul_f32_e32 v192, v176, v176
	v_fmac_f32_e32 v192, v177, v177
	v_fmac_f32_e32 v192, v178, v178
	v_fmac_f32_e32 v192, v179, v179
	v_fmac_f32_e32 v192, v180, v180
	v_fmac_f32_e32 v192, v181, v181
	v_fmac_f32_e32 v192, v182, v182
	v_fmac_f32_e32 v192, v183, v183
	v_fmac_f32_e32 v192, v184, v184
	v_fmac_f32_e32 v192, v185, v185
	v_fmac_f32_e32 v192, v186, v186
	v_fmac_f32_e32 v192, v187, v187
	v_fmac_f32_e32 v192, v188, v188
	v_fmac_f32_e32 v192, v189, v189
	v_fmac_f32_e32 v192, v190, v190
	v_fmac_f32_e32 v192, v191, v191
	v_mul_f32_e32 v194, v112, v176
	v_mul_f32_e32 v195, v113, v177
	v_mul_f32_e32 v196, v114, v178
	v_mul_f32_e32 v197, v115, v179
	v_mul_f32_e32 v198, v116, v180
	v_mul_f32_e32 v199, v117, v181
	v_mul_f32_e32 v200, v118, v182
	v_mul_f32_e32 v201, v119, v183
	v_mul_f32_e32 v202, v120, v184
	v_mul_f32_e32 v203, v121, v185
	v_mul_f32_e32 v204, v122, v186
	v_mul_f32_e32 v205, v123, v187
	v_mul_f32_e32 v206, v124, v188
	v_mul_f32_e32 v207, v125, v189
	v_mul_f32_e32 v208, v126, v190
	v_mul_f32_e32 v209, v127, v191
	s_nop 1
	v_add_f32_dpp v193, v192, v192 quad_perm:[1,0,3,2] row_mask:0xf bank_mask:0xf
	s_nop 1
	v_add_f32_dpp v192, v193, v193 quad_perm:[2,3,0,1] row_mask:0xf bank_mask:0xf
	s_nop 1
	v_add_f32_dpp v193, v192, v192 row_half_mirror row_mask:0xf bank_mask:0xf
	s_nop 1
	v_add_f32_dpp v192, v193, v193 row_mirror row_mask:0xf bank_mask:0xf
	s_nop 0
	v_readlane_b32 s0, v192, 0
	v_readlane_b32 s1, v192, 16
	v_readlane_b32 s6, v192, 32
	v_readlane_b32 s7, v192, 48
	s_nop 1
	v_mov_b32_e32 v193, s0
	v_add_f32_e32 v193, s1, v193
	v_add_f32_e32 v193, s6, v193
	v_add_f32_e32 v193, s7, v193
	v_fmamk_f32 v193, v193, 0x3a800000, v212
	v_rsq_f32_e32 v213, v193
	s_nop 0
	v_mul_f32_e32 v194, v213, v194
	v_mul_f32_e32 v195, v213, v195
	v_mul_f32_e32 v196, v213, v196
	v_mul_f32_e32 v197, v213, v197
	v_mul_f32_e32 v198, v213, v198
	v_mul_f32_e32 v199, v213, v199
	v_mul_f32_e32 v200, v213, v200
	v_mul_f32_e32 v201, v213, v201
	v_mul_f32_e32 v202, v213, v202
	v_mul_f32_e32 v203, v213, v203
	v_mul_f32_e32 v204, v213, v204
	v_mul_f32_e32 v205, v213, v205
	v_mul_f32_e32 v206, v213, v206
	v_mul_f32_e32 v207, v213, v207
	v_mul_f32_e32 v208, v213, v208
	v_mul_f32_e32 v209, v213, v209
	v_fmac_f32_e32 v80, v96, v194
	v_fmac_f32_e32 v81, v97, v195
	v_fmac_f32_e32 v82, v98, v196
	v_fmac_f32_e32 v83, v99, v197
	v_fmac_f32_e32 v84, v100, v198
	v_fmac_f32_e32 v85, v101, v199
	v_fmac_f32_e32 v86, v102, v200
	v_fmac_f32_e32 v87, v103, v201
	v_fmac_f32_e32 v88, v104, v202
	v_fmac_f32_e32 v89, v105, v203
	v_fmac_f32_e32 v90, v106, v204
	v_fmac_f32_e32 v91, v107, v205
	v_fmac_f32_e32 v92, v108, v206
	v_fmac_f32_e32 v93, v109, v207
	v_fmac_f32_e32 v94, v110, v208
	v_fmac_f32_e32 v95, v111, v209
	global_store_dwordx4 v210, v[80:83], s[20:21] nt
	global_store_dwordx4 v210, v[84:87], s[20:21] offset:1024 nt
	global_store_dwordx4 v210, v[88:91], s[20:21] offset:2048 nt
	global_store_dwordx4 v210, v[92:95], s[20:21] offset:3072 nt
	v_mul_f32_e32 v192, v80, v80
	v_fmac_f32_e32 v192, v81, v81
	v_fmac_f32_e32 v192, v82, v82
	v_fmac_f32_e32 v192, v83, v83
	v_fmac_f32_e32 v192, v84, v84
	v_fmac_f32_e32 v192, v85, v85
	v_fmac_f32_e32 v192, v86, v86
	v_fmac_f32_e32 v192, v87, v87
	v_fmac_f32_e32 v192, v88, v88
	v_fmac_f32_e32 v192, v89, v89
	v_fmac_f32_e32 v192, v90, v90
	v_fmac_f32_e32 v192, v91, v91
	v_fmac_f32_e32 v192, v92, v92
	v_fmac_f32_e32 v192, v93, v93
	v_fmac_f32_e32 v192, v94, v94
	v_fmac_f32_e32 v192, v95, v95
	s_nop 1
	v_add_f32_dpp v193, v192, v192 quad_perm:[1,0,3,2] row_mask:0xf bank_mask:0xf
	s_nop 1
	v_add_f32_dpp v192, v193, v193 quad_perm:[2,3,0,1] row_mask:0xf bank_mask:0xf
	s_nop 1
	v_add_f32_dpp v193, v192, v192 row_half_mirror row_mask:0xf bank_mask:0xf
	s_nop 1
	v_add_f32_dpp v192, v193, v193 row_mirror row_mask:0xf bank_mask:0xf
	s_nop 0
	v_readlane_b32 s0, v192, 0
	v_readlane_b32 s1, v192, 16
	v_readlane_b32 s6, v192, 32
	v_readlane_b32 s7, v192, 48
	s_nop 1
	v_mov_b32_e32 v193, s0
	v_add_f32_e32 v193, s1, v193
	v_add_f32_e32 v193, s6, v193
	v_add_f32_e32 v193, s7, v193
	v_fmamk_f32 v193, v193, 0x3a800000, v212
	v_rsq_f32_e32 v213, v193
	s_nop 0
	v_mul_f32_e32 v194, v80, v213
	v_mul_f32_e32 v195, v81, v213
	v_mul_f32_e32 v196, v82, v213
	v_mul_f32_e32 v197, v83, v213
	v_mul_f32_e32 v198, v84, v213
	v_mul_f32_e32 v199, v85, v213
	v_mul_f32_e32 v200, v86, v213
	v_mul_f32_e32 v201, v87, v213
	v_mul_f32_e32 v202, v88, v213
	v_mul_f32_e32 v203, v89, v213
	v_mul_f32_e32 v204, v90, v213
	v_mul_f32_e32 v205, v91, v213
	v_mul_f32_e32 v206, v92, v213
	v_mul_f32_e32 v207, v93, v213
	v_mul_f32_e32 v208, v94, v213
	v_mul_f32_e32 v209, v95, v213
	v_mul_f32_e32 v194, v128, v194
	v_mul_f32_e32 v195, v129, v195
	v_mul_f32_e32 v196, v130, v196
	v_mul_f32_e32 v197, v131, v197
	v_mul_f32_e32 v198, v132, v198
	v_mul_f32_e32 v199, v133, v199
	v_mul_f32_e32 v200, v134, v200
	v_mul_f32_e32 v201, v135, v201
	v_mul_f32_e32 v202, v136, v202
	v_mul_f32_e32 v203, v137, v203
	v_mul_f32_e32 v204, v138, v204
	v_mul_f32_e32 v205, v139, v205
	v_mul_f32_e32 v206, v140, v206
	v_mul_f32_e32 v207, v141, v207
	v_mul_f32_e32 v208, v142, v208
	v_mul_f32_e32 v209, v143, v209
	v_fma_f32 v194, v194, v160, v144
	v_fma_f32 v195, v195, v161, v145
	v_fma_f32 v196, v196, v162, v146
	v_fma_f32 v197, v197, v163, v147
	v_fma_f32 v198, v198, v164, v148
	v_fma_f32 v199, v199, v165, v149
	v_fma_f32 v200, v200, v166, v150
	v_fma_f32 v201, v201, v167, v151
	v_fma_f32 v202, v202, v168, v152
	v_fma_f32 v203, v203, v169, v153
	v_fma_f32 v204, v204, v170, v154
	v_fma_f32 v205, v205, v171, v155
	v_fma_f32 v206, v206, v172, v156
	v_fma_f32 v207, v207, v173, v157
	v_fma_f32 v208, v208, v174, v158
	v_fma_f32 v209, v209, v175, v159
	v_cvt_pk_bf16_f32 v194, v194, v195
	v_cvt_pk_bf16_f32 v195, v196, v197
	v_cvt_pk_bf16_f32 v196, v198, v199
	v_cvt_pk_bf16_f32 v197, v200, v201
	v_cvt_pk_bf16_f32 v198, v202, v203
	v_cvt_pk_bf16_f32 v199, v204, v205
	v_cvt_pk_bf16_f32 v200, v206, v207
	v_cvt_pk_bf16_f32 v201, v208, v209
	global_store_dwordx2 v211, v[194:195], s[36:37] nt
	global_store_dwordx2 v211, v[196:197], s[36:37] offset:512 nt
	global_store_dwordx2 v211, v[198:199], s[36:37] offset:1024 nt
	global_store_dwordx2 v211, v[200:201], s[36:37] offset:1536 nt
	s_add_u32 s18, s18, 0x400000
	s_addc_u32 s19, s19, 0
	s_add_u32 s20, s20, 0x400000
	s_addc_u32 s21, s21, 0
	s_add_u32 s24, s24, 0x200000
	s_addc_u32 s25, s25, 0
	s_add_u32 s36, s36, 0x200000
	s_addc_u32 s37, s37, 0
	s_branch .LBB0_313
.Lpost0_orig:
	v_lshlrev_b32_e32 v16, 2, v0
	v_and_b32_e32 v0, 64, v254
	v_add_u32_e32 v0, 64, v0
	v_xor_b32_e32 v1, 32, v254
	v_cmp_lt_i32_e32 vcc, v1, v0
	v_ashrrev_i32_e32 v17, 31, v16
	v_readlane_b32 s36, v255, 3
	v_cndmask_b32_e32 v1, v254, v1, vcc
	v_lshlrev_b32_e32 v48, 2, v1
	v_xor_b32_e32 v1, 16, v254
	v_cmp_lt_i32_e32 vcc, v1, v0
	v_lshlrev_b64 v[22:23], 2, v[16:17]
	v_readlane_b32 s44, v255, 11
	v_cndmask_b32_e32 v1, v254, v1, vcc
	v_lshlrev_b32_e32 v49, 2, v1
	v_xor_b32_e32 v1, 8, v254
	v_cmp_lt_i32_e32 vcc, v1, v0
	v_readlane_b32 s45, v255, 12
	s_mov_b64 s[0:1], 0x1000
	v_cndmask_b32_e32 v1, v254, v1, vcc
	v_lshlrev_b32_e32 v50, 2, v1
	v_xor_b32_e32 v1, 4, v254
	v_cmp_lt_i32_e32 vcc, v1, v0
	s_ashr_i32 s27, s26, 31
	s_lshl_b32 s6, s33, 4
	v_cndmask_b32_e32 v1, v254, v1, vcc
	v_lshlrev_b32_e32 v51, 2, v1
	v_xor_b32_e32 v1, 2, v254
	v_cmp_lt_i32_e32 vcc, v1, v0
	v_readlane_b32 s37, v255, 4
	v_readlane_b32 s38, v255, 5
	v_cndmask_b32_e32 v1, v254, v1, vcc
	v_lshlrev_b32_e32 v52, 2, v1
	v_xor_b32_e32 v1, 1, v254
	v_cmp_lt_i32_e32 vcc, v1, v0
	v_lshl_add_u64 v[24:25], s[36:37], 0, v[22:23]
	v_lshlrev_b64 v[18:19], 1, v[16:17]
	v_cndmask_b32_e32 v0, v254, v1, vcc
	v_lshlrev_b32_e32 v53, 2, v0
	v_lshl_add_u64 v[0:1], s[44:45], 0, v[22:23]
	v_lshl_add_u64 v[28:29], v[0:1], 0, s[0:1]
	s_lshl_b64 s[0:1], s[26:27], 13
	s_add_u32 s10, s62, s0
	s_addc_u32 s11, s63, s1
	s_add_i32 s0, s26, s82
	s_ashr_i32 s7, s6, 31
	s_ashr_i32 s1, s0, 31
	s_lshl_b64 s[12:13], s[6:7], 13
	s_lshl_b64 s[4:5], s[0:1], 11
	s_add_u32 s14, s60, s4
	s_addc_u32 s15, s61, s5
	s_lshl_b64 s[16:17], s[6:7], 11
	s_lshl_b64 s[4:5], s[26:27], 12
	s_add_u32 s18, s36, s4
	s_addc_u32 s19, s37, s5
	s_lshl_b64 s[20:21], s[6:7], 12
	s_lshl_b64 s[0:1], s[0:1], 12
	s_add_u32 s24, s30, s0
	s_addc_u32 s25, s31, s1
	s_add_u32 s36, s30, s4
	s_addc_u32 s37, s31, s5
	s_lshl_b64 s[0:1], s[26:27], 11
	v_readlane_b32 s39, v255, 6
	v_readlane_b32 s40, v255, 7
	v_readlane_b32 s41, v255, 8
	v_readlane_b32 s42, v255, 9
	v_readlane_b32 s43, v255, 10
	v_readlane_b32 s46, v255, 13
	v_readlane_b32 s47, v255, 14
	s_add_u32 s38, s60, s0
	v_lshl_add_u64 v[20:21], s[62:63], 0, v[18:19]
	v_lshl_add_u64 v[26:27], s[46:47], 0, v[22:23]
	s_addc_u32 s39, s61, s1
	s_mov_b64 s[40:41], 0x2000
	s_movk_i32 s0, 0x2000
	v_mov_b32_e32 v54, 0x358637bd
	s_mov_b32 s1, 0x800000
	s_mov_b64 s[42:43], 0xc000
	s_mov_b64 s[44:45], 0xd000
	s_mov_b32 s4, 0xd000
	s_mov_b32 s5, s26
	v_readlane_b32 s48, v255, 15
	v_readlane_b32 s49, v255, 16
	v_readlane_b32 s50, v255, 17
	v_readlane_b32 s51, v255, 18
	s_branch .LBB0_311

.LBB0_449:
	s_setprio 0
	s_and_b64 vcc, exec, s[8:9]
	s_barrier
	v_mbcnt_lo_u32_b32 v0, -1, 0
	v_mbcnt_hi_u32_b32 v0, -1, v0
	s_cbranch_vccnz .LBB0_454
	s_cmp_lg_u32 s33, 0x100
	s_cbranch_scc1 .Lpost1_orig
	v_mbcnt_lo_u32_b32 v210, -1, 0
	v_mbcnt_hi_u32_b32 v210, -1, v210
	v_readlane_b32 s40, v255, 13
	v_readlane_b32 s41, v255, 14
	v_lshlrev_b32_e32 v211, 3, v210
	v_lshlrev_b32_e32 v210, 4, v210
	v_mov_b32_e32 v212, 0x358637bd
	s_lshr_b32 s1, s26, 9
	s_and_b32 s4, s26, 0x1ff
	s_lshl_b32 s5, s1, 13
	s_add_u32 s5, s5, s4
	s_mul_i32 s6, s1, 0x3000
	s_add_u32 s38, s34, s6
	s_addc_u32 s39, s35, 0
	s_add_u32 s40, s40, 0x1000
	s_addc_u32 s41, s41, 0
	s_add_u32 s38, s38, 0xe000
	s_addc_u32 s39, s39, 0
	s_mul_i32 s6, s5, 0x3000
	s_add_u32 s10, s62, s6
	s_addc_u32 s11, s63, 0
	s_add_u32 s12, s10, 0x600000
	s_addc_u32 s13, s11, 0
	s_lshl_b32 s6, s5, 12
	s_add_u32 s14, s30, s6
	s_addc_u32 s15, s31, 0
	s_add_u32 s16, s14, 0x200000
	s_addc_u32 s17, s15, 0
	s_add_u32 s18, s30, s6
	s_addc_u32 s19, s31, 0
	s_add_u32 s20, s18, 0x200000
	s_addc_u32 s21, s19, 0
	s_mov_b32 s4, 0
	global_load_dwordx4 v[96:99], v210, s[40:41]
	global_load_dwordx4 v[100:103], v210, s[40:41] offset:1024
	global_load_dwordx4 v[104:107], v210, s[40:41] offset:2048
	global_load_dwordx4 v[108:111], v210, s[40:41] offset:3072
	global_load_dwordx4 v[112:115], v210, s[38:39]
	global_load_dwordx4 v[116:119], v210, s[38:39] offset:1024
	global_load_dwordx4 v[120:123], v210, s[38:39] offset:2048
	global_load_dwordx4 v[124:127], v210, s[38:39] offset:3072
	global_load_dwordx2 v[0:1], v211, s[10:11] nt
	global_load_dwordx2 v[2:3], v211, s[10:11] offset:512 nt
	global_load_dwordx2 v[4:5], v211, s[10:11] offset:1024 nt
	global_load_dwordx2 v[6:7], v211, s[10:11] offset:1536 nt
	global_load_dwordx4 v[16:19], v210, s[14:15] nt
	global_load_dwordx4 v[20:23], v210, s[14:15] offset:1024 nt
	global_load_dwordx4 v[24:27], v210, s[14:15] offset:2048 nt
	global_load_dwordx4 v[28:31], v210, s[14:15] offset:3072 nt
	global_load_dwordx2 v[8:9], v211, s[12:13] nt
	global_load_dwordx2 v[10:11], v211, s[12:13] offset:512 nt
	global_load_dwordx2 v[12:13], v211, s[12:13] offset:1024 nt
	global_load_dwordx2 v[14:15], v211, s[12:13] offset:1536 nt
	global_load_dwordx4 v[32:35], v210, s[16:17] nt
	global_load_dwordx4 v[36:39], v210, s[16:17] offset:1024 nt
	global_load_dwordx4 v[40:43], v210, s[16:17] offset:2048 nt
	global_load_dwordx4 v[44:47], v210, s[16:17] offset:3072 nt
	s_waitcnt vmcnt(0)
.Lpost1_loop:
	s_add_u32 s10, s10, 0xc00000
	s_addc_u32 s11, s11, 0
	s_add_u32 s12, s12, 0xc00000
	s_addc_u32 s13, s13, 0
	s_add_u32 s14, s14, 0x400000
	s_addc_u32 s15, s15, 0
	s_add_u32 s16, s16, 0x400000
	s_addc_u32 s17, s17, 0
	global_load_dwordx2 v[48:49], v211, s[10:11] nt
	global_load_dwordx2 v[50:51], v211, s[10:11] offset:512 nt
	global_load_dwordx2 v[52:53], v211, s[10:11] offset:1024 nt
	global_load_dwordx2 v[54:55], v211, s[10:11] offset:1536 nt
	global_load_dwordx4 v[64:67], v210, s[14:15] nt
	global_load_dwordx4 v[68:71], v210, s[14:15] offset:1024 nt
	global_load_dwordx4 v[72:75], v210, s[14:15] offset:2048 nt
	global_load_dwordx4 v[76:79], v210, s[14:15] offset:3072 nt
	global_load_dwordx2 v[56:57], v211, s[12:13] nt
	global_load_dwordx2 v[58:59], v211, s[12:13] offset:512 nt
	global_load_dwordx2 v[60:61], v211, s[12:13] offset:1024 nt
	global_load_dwordx2 v[62:63], v211, s[12:13] offset:1536 nt
	global_load_dwordx4 v[80:83], v210, s[16:17] nt
	global_load_dwordx4 v[84:87], v210, s[16:17] offset:1024 nt
	global_load_dwordx4 v[88:91], v210, s[16:17] offset:2048 nt
	global_load_dwordx4 v[92:95], v210, s[16:17] offset:3072 nt
	s_waitcnt vmcnt(32)
	v_lshlrev_b32_e32 v176, 16, v0
	v_and_b32_e32 v177, 0xffff0000, v0
	v_lshlrev_b32_e32 v178, 16, v1
	v_and_b32_e32 v179, 0xffff0000, v1
	v_lshlrev_b32_e32 v180, 16, v2
	v_and_b32_e32 v181, 0xffff0000, v2
	v_lshlrev_b32_e32 v182, 16, v3
	v_and_b32_e32 v183, 0xffff0000, v3
	v_lshlrev_b32_e32 v184, 16, v4
	v_and_b32_e32 v185, 0xffff0000, v4
	v_lshlrev_b32_e32 v186, 16, v5
	v_and_b32_e32 v187, 0xffff0000, v5
	v_lshlrev_b32_e32 v188, 16, v6
	v_and_b32_e32 v189, 0xffff0000, v6
	v_lshlrev_b32_e32 v190, 16, v7
	v_and_b32_e32 v191, 0xffff0000, v7
	v_mul_f32_e32 v192, v176, v176
	v_fmac_f32_e32 v192, v177, v177
	v_fmac_f32_e32 v192, v178, v178
	v_fmac_f32_e32 v192, v179, v179
	v_fmac_f32_e32 v192, v180, v180
	v_fmac_f32_e32 v192, v181, v181
	v_fmac_f32_e32 v192, v182, v182
	v_fmac_f32_e32 v192, v183, v183
	v_fmac_f32_e32 v192, v184, v184
	v_fmac_f32_e32 v192, v185, v185
	v_fmac_f32_e32 v192, v186, v186
	v_fmac_f32_e32 v192, v187, v187
	v_fmac_f32_e32 v192, v188, v188
	v_fmac_f32_e32 v192, v189, v189
	v_fmac_f32_e32 v192, v190, v190
	v_fmac_f32_e32 v192, v191, v191
	v_mul_f32_e32 v194, v112, v176
	v_mul_f32_e32 v195, v113, v177
	v_mul_f32_e32 v196, v114, v178
	v_mul_f32_e32 v197, v115, v179
	v_mul_f32_e32 v198, v116, v180
	v_mul_f32_e32 v199, v117, v181
	v_mul_f32_e32 v200, v118, v182
	v_mul_f32_e32 v201, v119, v183
	v_mul_f32_e32 v202, v120, v184
	v_mul_f32_e32 v203, v121, v185
	v_mul_f32_e32 v204, v122, v186
	v_mul_f32_e32 v205, v123, v187
	v_mul_f32_e32 v206, v124, v188
	v_mul_f32_e32 v207, v125, v189
	v_mul_f32_e32 v208, v126, v190
	v_mul_f32_e32 v209, v127, v191
	s_nop 1
	v_add_f32_dpp v193, v192, v192 quad_perm:[1,0,3,2] row_mask:0xf bank_mask:0xf
	s_nop 1
	v_add_f32_dpp v192, v193, v193 quad_perm:[2,3,0,1] row_mask:0xf bank_mask:0xf
	s_nop 1
	v_add_f32_dpp v193, v192, v192 row_half_mirror row_mask:0xf bank_mask:0xf
	s_nop 1
	v_add_f32_dpp v192, v193, v193 row_mirror row_mask:0xf bank_mask:0xf
	s_nop 0
	v_readlane_b32 s0, v192, 0
	v_readlane_b32 s1, v192, 16
	v_readlane_b32 s6, v192, 32
	v_readlane_b32 s7, v192, 48
	s_nop 1
	v_mov_b32_e32 v193, s0
	v_add_f32_e32 v193, s1, v193
	v_add_f32_e32 v193, s6, v193
	v_add_f32_e32 v193, s7, v193
	v_fmamk_f32 v193, v193, 0x3a800000, v212
	v_rsq_f32_e32 v213, v193
	s_nop 0
	v_mul_f32_e32 v194, v213, v194
	v_mul_f32_e32 v195, v213, v195
	v_mul_f32_e32 v196, v213, v196
	v_mul_f32_e32 v197, v213, v197
	v_mul_f32_e32 v198, v213, v198
	v_mul_f32_e32 v199, v213, v199
	v_mul_f32_e32 v200, v213, v200
	v_mul_f32_e32 v201, v213, v201
	v_mul_f32_e32 v202, v213, v202
	v_mul_f32_e32 v203, v213, v203
	v_mul_f32_e32 v204, v213, v204
	v_mul_f32_e32 v205, v213, v205
	v_mul_f32_e32 v206, v213, v206
	v_mul_f32_e32 v207, v213, v207
	v_mul_f32_e32 v208, v213, v208
	v_mul_f32_e32 v209, v213, v209
	v_fmac_f32_e32 v16, v96, v194
	v_fmac_f32_e32 v17, v97, v195
	v_fmac_f32_e32 v18, v98, v196
	v_fmac_f32_e32 v19, v99, v197
	v_fmac_f32_e32 v20, v100, v198
	v_fmac_f32_e32 v21, v101, v199
	v_fmac_f32_e32 v22, v102, v200
	v_fmac_f32_e32 v23, v103, v201
	v_fmac_f32_e32 v24, v104, v202
	v_fmac_f32_e32 v25, v105, v203
	v_fmac_f32_e32 v26, v106, v204
	v_fmac_f32_e32 v27, v107, v205
	v_fmac_f32_e32 v28, v108, v206
	v_fmac_f32_e32 v29, v109, v207
	v_fmac_f32_e32 v30, v110, v208
	v_fmac_f32_e32 v31, v111, v209
	global_store_dwordx4 v210, v[16:19], s[18:19] nt
	global_store_dwordx4 v210, v[20:23], s[18:19] offset:1024 nt
	global_store_dwordx4 v210, v[24:27], s[18:19] offset:2048 nt
	global_store_dwordx4 v210, v[28:31], s[18:19] offset:3072 nt
	s_waitcnt vmcnt(20)
	v_lshlrev_b32_e32 v176, 16, v8
	v_and_b32_e32 v177, 0xffff0000, v8
	v_lshlrev_b32_e32 v178, 16, v9
	v_and_b32_e32 v179, 0xffff0000, v9
	v_lshlrev_b32_e32 v180, 16, v10
	v_and_b32_e32 v181, 0xffff0000, v10
	v_lshlrev_b32_e32 v182, 16, v11
	v_and_b32_e32 v183, 0xffff0000, v11
	v_lshlrev_b32_e32 v184, 16, v12
	v_and_b32_e32 v185, 0xffff0000, v12
	v_lshlrev_b32_e32 v186, 16, v13
	v_and_b32_e32 v187, 0xffff0000, v13
	v_lshlrev_b32_e32 v188, 16, v14
	v_and_b32_e32 v189, 0xffff0000, v14
	v_lshlrev_b32_e32 v190, 16, v15
	v_and_b32_e32 v191, 0xffff0000, v15
	v_mul_f32_e32 v192, v176, v176
	v_fmac_f32_e32 v192, v177, v177
	v_fmac_f32_e32 v192, v178, v178
	v_fmac_f32_e32 v192, v179, v179
	v_fmac_f32_e32 v192, v180, v180
	v_fmac_f32_e32 v192, v181, v181
	v_fmac_f32_e32 v192, v182, v182
	v_fmac_f32_e32 v192, v183, v183
	v_fmac_f32_e32 v192, v184, v184
	v_fmac_f32_e32 v192, v185, v185
	v_fmac_f32_e32 v192, v186, v186
	v_fmac_f32_e32 v192, v187, v187
	v_fmac_f32_e32 v192, v188, v188
	v_fmac_f32_e32 v192, v189, v189
	v_fmac_f32_e32 v192, v190, v190
	v_fmac_f32_e32 v192, v191, v191
	v_mul_f32_e32 v194, v112, v176
	v_mul_f32_e32 v195, v113, v177
	v_mul_f32_e32 v196, v114, v178
	v_mul_f32_e32 v197, v115, v179
	v_mul_f32_e32 v198, v116, v180
	v_mul_f32_e32 v199, v117, v181
	v_mul_f32_e32 v200, v118, v182
	v_mul_f32_e32 v201, v119, v183
	v_mul_f32_e32 v202, v120, v184
	v_mul_f32_e32 v203, v121, v185
	v_mul_f32_e32 v204, v122, v186
	v_mul_f32_e32 v205, v123, v187
	v_mul_f32_e32 v206, v124, v188
	v_mul_f32_e32 v207, v125, v189
	v_mul_f32_e32 v208, v126, v190
	v_mul_f32_e32 v209, v127, v191
	s_nop 1
	v_add_f32_dpp v193, v192, v192 quad_perm:[1,0,3,2] row_mask:0xf bank_mask:0xf
	s_nop 1
	v_add_f32_dpp v192, v193, v193 quad_perm:[2,3,0,1] row_mask:0xf bank_mask:0xf
	s_nop 1
	v_add_f32_dpp v193, v192, v192 row_half_mirror row_mask:0xf bank_mask:0xf
	s_nop 1
	v_add_f32_dpp v192, v193, v193 row_mirror row_mask:0xf bank_mask:0xf
	s_nop 0
	v_readlane_b32 s0, v192, 0
	v_readlane_b32 s1, v192, 16
	v_readlane_b32 s6, v192, 32
	v_readlane_b32 s7, v192, 48
	s_nop 1
	v_mov_b32_e32 v193, s0
	v_add_f32_e32 v193, s1, v193
	v_add_f32_e32 v193, s6, v193
	v_add_f32_e32 v193, s7, v193
	v_fmamk_f32 v193, v193, 0x3a800000, v212
	v_rsq_f32_e32 v213, v193
	s_nop 0
	v_mul_f32_e32 v194, v213, v194
	v_mul_f32_e32 v195, v213, v195
	v_mul_f32_e32 v196, v213, v196
	v_mul_f32_e32 v197, v213, v197
	v_mul_f32_e32 v198, v213, v198
	v_mul_f32_e32 v199, v213, v199
	v_mul_f32_e32 v200, v213, v200
	v_mul_f32_e32 v201, v213, v201
	v_mul_f32_e32 v202, v213, v202
	v_mul_f32_e32 v203, v213, v203
	v_mul_f32_e32 v204, v213, v204
	v_mul_f32_e32 v205, v213, v205
	v_mul_f32_e32 v206, v213, v206
	v_mul_f32_e32 v207, v213, v207
	v_mul_f32_e32 v208, v213, v208
	v_mul_f32_e32 v209, v213, v209
	v_fmac_f32_e32 v32, v96, v194
	v_fmac_f32_e32 v33, v97, v195
	v_fmac_f32_e32 v34, v98, v196
	v_fmac_f32_e32 v35, v99, v197
	v_fmac_f32_e32 v36, v100, v198
	v_fmac_f32_e32 v37, v101, v199
	v_fmac_f32_e32 v38, v102, v200
	v_fmac_f32_e32 v39, v103, v201
	v_fmac_f32_e32 v40, v104, v202
	v_fmac_f32_e32 v41, v105, v203
	v_fmac_f32_e32 v42, v106, v204
	v_fmac_f32_e32 v43, v107, v205
	v_fmac_f32_e32 v44, v108, v206
	v_fmac_f32_e32 v45, v109, v207
	v_fmac_f32_e32 v46, v110, v208
	v_fmac_f32_e32 v47, v111, v209
	global_store_dwordx4 v210, v[32:35], s[20:21] nt
	global_store_dwordx4 v210, v[36:39], s[20:21] offset:1024 nt
	global_store_dwordx4 v210, v[40:43], s[20:21] offset:2048 nt
	global_store_dwordx4 v210, v[44:47], s[20:21] offset:3072 nt
	s_add_u32 s18, s18, 0x400000
	s_addc_u32 s19, s19, 0
	s_add_u32 s20, s20, 0x400000
	s_addc_u32 s21, s21, 0
	s_cmp_eq_u32 s4, 3
	s_cbranch_scc1 .Lpost1_last
	s_add_u32 s10, s10, 0xc00000
	s_addc_u32 s11, s11, 0
	s_add_u32 s12, s12, 0xc00000
	s_addc_u32 s13, s13, 0
	s_add_u32 s14, s14, 0x400000
	s_addc_u32 s15, s15, 0
	s_add_u32 s16, s16, 0x400000
	s_addc_u32 s17, s17, 0
	global_load_dwordx2 v[0:1], v211, s[10:11] nt
	global_load_dwordx2 v[2:3], v211, s[10:11] offset:512 nt
	global_load_dwordx2 v[4:5], v211, s[10:11] offset:1024 nt
	global_load_dwordx2 v[6:7], v211, s[10:11] offset:1536 nt
	global_load_dwordx4 v[16:19], v210, s[14:15] nt
	global_load_dwordx4 v[20:23], v210, s[14:15] offset:1024 nt
	global_load_dwordx4 v[24:27], v210, s[14:15] offset:2048 nt
	global_load_dwordx4 v[28:31], v210, s[14:15] offset:3072 nt
	global_load_dwordx2 v[8:9], v211, s[12:13] nt
	global_load_dwordx2 v[10:11], v211, s[12:13] offset:512 nt
	global_load_dwordx2 v[12:13], v211, s[12:13] offset:1024 nt
	global_load_dwordx2 v[14:15], v211, s[12:13] offset:1536 nt
	global_load_dwordx4 v[32:35], v210, s[16:17] nt
	global_load_dwordx4 v[36:39], v210, s[16:17] offset:1024 nt
	global_load_dwordx4 v[40:43], v210, s[16:17] offset:2048 nt
	global_load_dwordx4 v[44:47], v210, s[16:17] offset:3072 nt
	s_waitcnt vmcnt(32)
	v_lshlrev_b32_e32 v176, 16, v48
	v_and_b32_e32 v177, 0xffff0000, v48
	v_lshlrev_b32_e32 v178, 16, v49
	v_and_b32_e32 v179, 0xffff0000, v49
	v_lshlrev_b32_e32 v180, 16, v50
	v_and_b32_e32 v181, 0xffff0000, v50
	v_lshlrev_b32_e32 v182, 16, v51
	v_and_b32_e32 v183, 0xffff0000, v51
	v_lshlrev_b32_e32 v184, 16, v52
	v_and_b32_e32 v185, 0xffff0000, v52
	v_lshlrev_b32_e32 v186, 16, v53
	v_and_b32_e32 v187, 0xffff0000, v53
	v_lshlrev_b32_e32 v188, 16, v54
	v_and_b32_e32 v189, 0xffff0000, v54
	v_lshlrev_b32_e32 v190, 16, v55
	v_and_b32_e32 v191, 0xffff0000, v55
	v_mul_f32_e32 v192, v176, v176
	v_fmac_f32_e32 v192, v177, v177
	v_fmac_f32_e32 v192, v178, v178
	v_fmac_f32_e32 v192, v179, v179
	v_fmac_f32_e32 v192, v180, v180
	v_fmac_f32_e32 v192, v181, v181
	v_fmac_f32_e32 v192, v182, v182
	v_fmac_f32_e32 v192, v183, v183
	v_fmac_f32_e32 v192, v184, v184
	v_fmac_f32_e32 v192, v185, v185
	v_fmac_f32_e32 v192, v186, v186
	v_fmac_f32_e32 v192, v187, v187
	v_fmac_f32_e32 v192, v188, v188
	v_fmac_f32_e32 v192, v189, v189
	v_fmac_f32_e32 v192, v190, v190
	v_fmac_f32_e32 v192, v191, v191
	v_mul_f32_e32 v194, v112, v176
	v_mul_f32_e32 v195, v113, v177
	v_mul_f32_e32 v196, v114, v178
	v_mul_f32_e32 v197, v115, v179
	v_mul_f32_e32 v198, v116, v180
	v_mul_f32_e32 v199, v117, v181
	v_mul_f32_e32 v200, v118, v182
	v_mul_f32_e32 v201, v119, v183
	v_mul_f32_e32 v202, v120, v184
	v_mul_f32_e32 v203, v121, v185
	v_mul_f32_e32 v204, v122, v186
	v_mul_f32_e32 v205, v123, v187
	v_mul_f32_e32 v206, v124, v188
	v_mul_f32_e32 v207, v125, v189
	v_mul_f32_e32 v208, v126, v190
	v_mul_f32_e32 v209, v127, v191
	s_nop 1
	v_add_f32_dpp v193, v192, v192 quad_perm:[1,0,3,2] row_mask:0xf bank_mask:0xf
	s_nop 1
	v_add_f32_dpp v192, v193, v193 quad_perm:[2,3,0,1] row_mask:0xf bank_mask:0xf
	s_nop 1
	v_add_f32_dpp v193, v192, v192 row_half_mirror row_mask:0xf bank_mask:0xf
	s_nop 1
	v_add_f32_dpp v192, v193, v193 row_mirror row_mask:0xf bank_mask:0xf
	s_nop 0
	v_readlane_b32 s0, v192, 0
	v_readlane_b32 s1, v192, 16
	v_readlane_b32 s6, v192, 32
	v_readlane_b32 s7, v192, 48
	s_nop 1
	v_mov_b32_e32 v193, s0
	v_add_f32_e32 v193, s1, v193
	v_add_f32_e32 v193, s6, v193
	v_add_f32_e32 v193, s7, v193
	v_fmamk_f32 v193, v193, 0x3a800000, v212
	v_rsq_f32_e32 v213, v193
	s_nop 0
	v_mul_f32_e32 v194, v213, v194
	v_mul_f32_e32 v195, v213, v195
	v_mul_f32_e32 v196, v213, v196
	v_mul_f32_e32 v197, v213, v197
	v_mul_f32_e32 v198, v213, v198
	v_mul_f32_e32 v199, v213, v199
	v_mul_f32_e32 v200, v213, v200
	v_mul_f32_e32 v201, v213, v201
	v_mul_f32_e32 v202, v213, v202
	v_mul_f32_e32 v203, v213, v203
	v_mul_f32_e32 v204, v213, v204
	v_mul_f32_e32 v205, v213, v205
	v_mul_f32_e32 v206, v213, v206
	v_mul_f32_e32 v207, v213, v207
	v_mul_f32_e32 v208, v213, v208
	v_mul_f32_e32 v209, v213, v209
	v_fmac_f32_e32 v64, v96, v194
	v_fmac_f32_e32 v65, v97, v195
	v_fmac_f32_e32 v66, v98, v196
	v_fmac_f32_e32 v67, v99, v197
	v_fmac_f32_e32 v68, v100, v198
	v_fmac_f32_e32 v69, v101, v199
	v_fmac_f32_e32 v70, v102, v200
	v_fmac_f32_e32 v71, v103, v201
	v_fmac_f32_e32 v72, v104, v202
	v_fmac_f32_e32 v73, v105, v203
	v_fmac_f32_e32 v74, v106, v204
	v_fmac_f32_e32 v75, v107, v205
	v_fmac_f32_e32 v76, v108, v206
	v_fmac_f32_e32 v77, v109, v207
	v_fmac_f32_e32 v78, v110, v208
	v_fmac_f32_e32 v79, v111, v209
	global_store_dwordx4 v210, v[64:67], s[18:19] nt
	global_store_dwordx4 v210, v[68:71], s[18:19] offset:1024 nt
	global_store_dwordx4 v210, v[72:75], s[18:19] offset:2048 nt
	global_store_dwordx4 v210, v[76:79], s[18:19] offset:3072 nt
	s_waitcnt vmcnt(20)
	v_lshlrev_b32_e32 v176, 16, v56
	v_and_b32_e32 v177, 0xffff0000, v56
	v_lshlrev_b32_e32 v178, 16, v57
	v_and_b32_e32 v179, 0xffff0000, v57
	v_lshlrev_b32_e32 v180, 16, v58
	v_and_b32_e32 v181, 0xffff0000, v58
	v_lshlrev_b32_e32 v182, 16, v59
	v_and_b32_e32 v183, 0xffff0000, v59
	v_lshlrev_b32_e32 v184, 16, v60
	v_and_b32_e32 v185, 0xffff0000, v60
	v_lshlrev_b32_e32 v186, 16, v61
	v_and_b32_e32 v187, 0xffff0000, v61
	v_lshlrev_b32_e32 v188, 16, v62
	v_and_b32_e32 v189, 0xffff0000, v62
	v_lshlrev_b32_e32 v190, 16, v63
	v_and_b32_e32 v191, 0xffff0000, v63
	v_mul_f32_e32 v192, v176, v176
	v_fmac_f32_e32 v192, v177, v177
	v_fmac_f32_e32 v192, v178, v178
	v_fmac_f32_e32 v192, v179, v179
	v_fmac_f32_e32 v192, v180, v180
	v_fmac_f32_e32 v192, v181, v181
	v_fmac_f32_e32 v192, v182, v182
	v_fmac_f32_e32 v192, v183, v183
	v_fmac_f32_e32 v192, v184, v184
	v_fmac_f32_e32 v192, v185, v185
	v_fmac_f32_e32 v192, v186, v186
	v_fmac_f32_e32 v192, v187, v187
	v_fmac_f32_e32 v192, v188, v188
	v_fmac_f32_e32 v192, v189, v189
	v_fmac_f32_e32 v192, v190, v190
	v_fmac_f32_e32 v192, v191, v191
	v_mul_f32_e32 v194, v112, v176
	v_mul_f32_e32 v195, v113, v177
	v_mul_f32_e32 v196, v114, v178
	v_mul_f32_e32 v197, v115, v179
	v_mul_f32_e32 v198, v116, v180
	v_mul_f32_e32 v199, v117, v181
	v_mul_f32_e32 v200, v118, v182
	v_mul_f32_e32 v201, v119, v183
	v_mul_f32_e32 v202, v120, v184
	v_mul_f32_e32 v203, v121, v185
	v_mul_f32_e32 v204, v122, v186
	v_mul_f32_e32 v205, v123, v187
	v_mul_f32_e32 v206, v124, v188
	v_mul_f32_e32 v207, v125, v189
	v_mul_f32_e32 v208, v126, v190
	v_mul_f32_e32 v209, v127, v191
	s_nop 1
	v_add_f32_dpp v193, v192, v192 quad_perm:[1,0,3,2] row_mask:0xf bank_mask:0xf
	s_nop 1
	v_add_f32_dpp v192, v193, v193 quad_perm:[2,3,0,1] row_mask:0xf bank_mask:0xf
	s_nop 1
	v_add_f32_dpp v193, v192, v192 row_half_mirror row_mask:0xf bank_mask:0xf
	s_nop 1
	v_add_f32_dpp v192, v193, v193 row_mirror row_mask:0xf bank_mask:0xf
	s_nop 0
	v_readlane_b32 s0, v192, 0
	v_readlane_b32 s1, v192, 16
	v_readlane_b32 s6, v192, 32
	v_readlane_b32 s7, v192, 48
	s_nop 1
	v_mov_b32_e32 v193, s0
	v_add_f32_e32 v193, s1, v193
	v_add_f32_e32 v193, s6, v193
	v_add_f32_e32 v193, s7, v193
	v_fmamk_f32 v193, v193, 0x3a800000, v212
	v_rsq_f32_e32 v213, v193
	s_nop 0
	v_mul_f32_e32 v194, v213, v194
	v_mul_f32_e32 v195, v213, v195
	v_mul_f32_e32 v196, v213, v196
	v_mul_f32_e32 v197, v213, v197
	v_mul_f32_e32 v198, v213, v198
	v_mul_f32_e32 v199, v213, v199
	v_mul_f32_e32 v200, v213, v200
	v_mul_f32_e32 v201, v213, v201
	v_mul_f32_e32 v202, v213, v202
	v_mul_f32_e32 v203, v213, v203
	v_mul_f32_e32 v204, v213, v204
	v_mul_f32_e32 v205, v213, v205
	v_mul_f32_e32 v206, v213, v206
	v_mul_f32_e32 v207, v213, v207
	v_mul_f32_e32 v208, v213, v208
	v_mul_f32_e32 v209, v213, v209
	v_fmac_f32_e32 v80, v96, v194
	v_fmac_f32_e32 v81, v97, v195
	v_fmac_f32_e32 v82, v98, v196
	v_fmac_f32_e32 v83, v99, v197
	v_fmac_f32_e32 v84, v100, v198
	v_fmac_f32_e32 v85, v101, v199
	v_fmac_f32_e32 v86, v102, v200
	v_fmac_f32_e32 v87, v103, v201
	v_fmac_f32_e32 v88, v104, v202
	v_fmac_f32_e32 v89, v105, v203
	v_fmac_f32_e32 v90, v106, v204
	v_fmac_f32_e32 v91, v107, v205
	v_fmac_f32_e32 v92, v108, v206
	v_fmac_f32_e32 v93, v109, v207
	v_fmac_f32_e32 v94, v110, v208
	v_fmac_f32_e32 v95, v111, v209
	global_store_dwordx4 v210, v[80:83], s[20:21] nt
	global_store_dwordx4 v210, v[84:87], s[20:21] offset:1024 nt
	global_store_dwordx4 v210, v[88:91], s[20:21] offset:2048 nt
	global_store_dwordx4 v210, v[92:95], s[20:21] offset:3072 nt
	s_add_u32 s18, s18, 0x400000
	s_addc_u32 s19, s19, 0
	s_add_u32 s20, s20, 0x400000
	s_addc_u32 s21, s21, 0
	s_add_u32 s4, s4, 1
	s_branch .Lpost1_loop
.Lpost1_last:
	s_waitcnt vmcnt(16)
	v_lshlrev_b32_e32 v176, 16, v48
	v_and_b32_e32 v177, 0xffff0000, v48
	v_lshlrev_b32_e32 v178, 16, v49
	v_and_b32_e32 v179, 0xffff0000, v49
	v_lshlrev_b32_e32 v180, 16, v50
	v_and_b32_e32 v181, 0xffff0000, v50
	v_lshlrev_b32_e32 v182, 16, v51
	v_and_b32_e32 v183, 0xffff0000, v51
	v_lshlrev_b32_e32 v184, 16, v52
	v_and_b32_e32 v185, 0xffff0000, v52
	v_lshlrev_b32_e32 v186, 16, v53
	v_and_b32_e32 v187, 0xffff0000, v53
	v_lshlrev_b32_e32 v188, 16, v54
	v_and_b32_e32 v189, 0xffff0000, v54
	v_lshlrev_b32_e32 v190, 16, v55
	v_and_b32_e32 v191, 0xffff0000, v55
	v_mul_f32_e32 v192, v176, v176
	v_fmac_f32_e32 v192, v177, v177
	v_fmac_f32_e32 v192, v178, v178
	v_fmac_f32_e32 v192, v179, v179
	v_fmac_f32_e32 v192, v180, v180
	v_fmac_f32_e32 v192, v181, v181
	v_fmac_f32_e32 v192, v182, v182
	v_fmac_f32_e32 v192, v183, v183
	v_fmac_f32_e32 v192, v184, v184
	v_fmac_f32_e32 v192, v185, v185
	v_fmac_f32_e32 v192, v186, v186
	v_fmac_f32_e32 v192, v187, v187
	v_fmac_f32_e32 v192, v188, v188
	v_fmac_f32_e32 v192, v189, v189
	v_fmac_f32_e32 v192, v190, v190
	v_fmac_f32_e32 v192, v191, v191
	v_mul_f32_e32 v194, v112, v176
	v_mul_f32_e32 v195, v113, v177
	v_mul_f32_e32 v196, v114, v178
	v_mul_f32_e32 v197, v115, v179
	v_mul_f32_e32 v198, v116, v180
	v_mul_f32_e32 v199, v117, v181
	v_mul_f32_e32 v200, v118, v182
	v_mul_f32_e32 v201, v119, v183
	v_mul_f32_e32 v202, v120, v184
	v_mul_f32_e32 v203, v121, v185
	v_mul_f32_e32 v204, v122, v186
	v_mul_f32_e32 v205, v123, v187
	v_mul_f32_e32 v206, v124, v188
	v_mul_f32_e32 v207, v125, v189
	v_mul_f32_e32 v208, v126, v190
	v_mul_f32_e32 v209, v127, v191
	s_nop 1
	v_add_f32_dpp v193, v192, v192 quad_perm:[1,0,3,2] row_mask:0xf bank_mask:0xf
	s_nop 1
	v_add_f32_dpp v192, v193, v193 quad_perm:[2,3,0,1] row_mask:0xf bank_mask:0xf
	s_nop 1
	v_add_f32_dpp v193, v192, v192 row_half_mirror row_mask:0xf bank_mask:0xf
	s_nop 1
	v_add_f32_dpp v192, v193, v193 row_mirror row_mask:0xf bank_mask:0xf
	s_nop 0
	v_readlane_b32 s0, v192, 0
	v_readlane_b32 s1, v192, 16
	v_readlane_b32 s6, v192, 32
	v_readlane_b32 s7, v192, 48
	s_nop 1
	v_mov_b32_e32 v193, s0
	v_add_f32_e32 v193, s1, v193
	v_add_f32_e32 v193, s6, v193
	v_add_f32_e32 v193, s7, v193
	v_fmamk_f32 v193, v193, 0x3a800000, v212
	v_rsq_f32_e32 v213, v193
	s_nop 0
	v_mul_f32_e32 v194, v213, v194
	v_mul_f32_e32 v195, v213, v195
	v_mul_f32_e32 v196, v213, v196
	v_mul_f32_e32 v197, v213, v197
	v_mul_f32_e32 v198, v213, v198
	v_mul_f32_e32 v199, v213, v199
	v_mul_f32_e32 v200, v213, v200
	v_mul_f32_e32 v201, v213, v201
	v_mul_f32_e32 v202, v213, v202
	v_mul_f32_e32 v203, v213, v203
	v_mul_f32_e32 v204, v213, v204
	v_mul_f32_e32 v205, v213, v205
	v_mul_f32_e32 v206, v213, v206
	v_mul_f32_e32 v207, v213, v207
	v_mul_f32_e32 v208, v213, v208
	v_mul_f32_e32 v209, v213, v209
	v_fmac_f32_e32 v64, v96, v194
	v_fmac_f32_e32 v65, v97, v195
	v_fmac_f32_e32 v66, v98, v196
	v_fmac_f32_e32 v67, v99, v197
	v_fmac_f32_e32 v68, v100, v198
	v_fmac_f32_e32 v69, v101, v199
	v_fmac_f32_e32 v70, v102, v200
	v_fmac_f32_e32 v71, v103, v201
	v_fmac_f32_e32 v72, v104, v202
	v_fmac_f32_e32 v73, v105, v203
	v_fmac_f32_e32 v74, v106, v204
	v_fmac_f32_e32 v75, v107, v205
	v_fmac_f32_e32 v76, v108, v206
	v_fmac_f32_e32 v77, v109, v207
	v_fmac_f32_e32 v78, v110, v208
	v_fmac_f32_e32 v79, v111, v209
	global_store_dwordx4 v210, v[64:67], s[18:19] nt
	global_store_dwordx4 v210, v[68:71], s[18:19] offset:1024 nt
	global_store_dwordx4 v210, v[72:75], s[18:19] offset:2048 nt
	global_store_dwordx4 v210, v[76:79], s[18:19] offset:3072 nt
	s_waitcnt vmcnt(4)
	v_lshlrev_b32_e32 v176, 16, v56
	v_and_b32_e32 v177, 0xffff0000, v56
	v_lshlrev_b32_e32 v178, 16, v57
	v_and_b32_e32 v179, 0xffff0000, v57
	v_lshlrev_b32_e32 v180, 16, v58
	v_and_b32_e32 v181, 0xffff0000, v58
	v_lshlrev_b32_e32 v182, 16, v59
	v_and_b32_e32 v183, 0xffff0000, v59
	v_lshlrev_b32_e32 v184, 16, v60
	v_and_b32_e32 v185, 0xffff0000, v60
	v_lshlrev_b32_e32 v186, 16, v61
	v_and_b32_e32 v187, 0xffff0000, v61
	v_lshlrev_b32_e32 v188, 16, v62
	v_and_b32_e32 v189, 0xffff0000, v62
	v_lshlrev_b32_e32 v190, 16, v63
	v_and_b32_e32 v191, 0xffff0000, v63
	v_mul_f32_e32 v192, v176, v176
	v_fmac_f32_e32 v192, v177, v177
	v_fmac_f32_e32 v192, v178, v178
	v_fmac_f32_e32 v192, v179, v179
	v_fmac_f32_e32 v192, v180, v180
	v_fmac_f32_e32 v192, v181, v181
	v_fmac_f32_e32 v192, v182, v182
	v_fmac_f32_e32 v192, v183, v183
	v_fmac_f32_e32 v192, v184, v184
	v_fmac_f32_e32 v192, v185, v185
	v_fmac_f32_e32 v192, v186, v186
	v_fmac_f32_e32 v192, v187, v187
	v_fmac_f32_e32 v192, v188, v188
	v_fmac_f32_e32 v192, v189, v189
	v_fmac_f32_e32 v192, v190, v190
	v_fmac_f32_e32 v192, v191, v191
	v_mul_f32_e32 v194, v112, v176
	v_mul_f32_e32 v195, v113, v177
	v_mul_f32_e32 v196, v114, v178
	v_mul_f32_e32 v197, v115, v179
	v_mul_f32_e32 v198, v116, v180
	v_mul_f32_e32 v199, v117, v181
	v_mul_f32_e32 v200, v118, v182
	v_mul_f32_e32 v201, v119, v183
	v_mul_f32_e32 v202, v120, v184
	v_mul_f32_e32 v203, v121, v185
	v_mul_f32_e32 v204, v122, v186
	v_mul_f32_e32 v205, v123, v187
	v_mul_f32_e32 v206, v124, v188
	v_mul_f32_e32 v207, v125, v189
	v_mul_f32_e32 v208, v126, v190
	v_mul_f32_e32 v209, v127, v191
	s_nop 1
	v_add_f32_dpp v193, v192, v192 quad_perm:[1,0,3,2] row_mask:0xf bank_mask:0xf
	s_nop 1
	v_add_f32_dpp v192, v193, v193 quad_perm:[2,3,0,1] row_mask:0xf bank_mask:0xf
	s_nop 1
	v_add_f32_dpp v193, v192, v192 row_half_mirror row_mask:0xf bank_mask:0xf
	s_nop 1
	v_add_f32_dpp v192, v193, v193 row_mirror row_mask:0xf bank_mask:0xf
	s_nop 0
	v_readlane_b32 s0, v192, 0
	v_readlane_b32 s1, v192, 16
	v_readlane_b32 s6, v192, 32
	v_readlane_b32 s7, v192, 48
	s_nop 1
	v_mov_b32_e32 v193, s0
	v_add_f32_e32 v193, s1, v193
	v_add_f32_e32 v193, s6, v193
	v_add_f32_e32 v193, s7, v193
	v_fmamk_f32 v193, v193, 0x3a800000, v212
	v_rsq_f32_e32 v213, v193
	s_nop 0
	v_mul_f32_e32 v194, v213, v194
	v_mul_f32_e32 v195, v213, v195
	v_mul_f32_e32 v196, v213, v196
	v_mul_f32_e32 v197, v213, v197
	v_mul_f32_e32 v198, v213, v198
	v_mul_f32_e32 v199, v213, v199
	v_mul_f32_e32 v200, v213, v200
	v_mul_f32_e32 v201, v213, v201
	v_mul_f32_e32 v202, v213, v202
	v_mul_f32_e32 v203, v213, v203
	v_mul_f32_e32 v204, v213, v204
	v_mul_f32_e32 v205, v213, v205
	v_mul_f32_e32 v206, v213, v206
	v_mul_f32_e32 v207, v213, v207
	v_mul_f32_e32 v208, v213, v208
	v_mul_f32_e32 v209, v213, v209
	v_fmac_f32_e32 v80, v96, v194
	v_fmac_f32_e32 v81, v97, v195
	v_fmac_f32_e32 v82, v98, v196
	v_fmac_f32_e32 v83, v99, v197
	v_fmac_f32_e32 v84, v100, v198
	v_fmac_f32_e32 v85, v101, v199
	v_fmac_f32_e32 v86, v102, v200
	v_fmac_f32_e32 v87, v103, v201
	v_fmac_f32_e32 v88, v104, v202
	v_fmac_f32_e32 v89, v105, v203
	v_fmac_f32_e32 v90, v106, v204
	v_fmac_f32_e32 v91, v107, v205
	v_fmac_f32_e32 v92, v108, v206
	v_fmac_f32_e32 v93, v109, v207
	v_fmac_f32_e32 v94, v110, v208
	v_fmac_f32_e32 v95, v111, v209
	global_store_dwordx4 v210, v[80:83], s[20:21] nt
	global_store_dwordx4 v210, v[84:87], s[20:21] offset:1024 nt
	global_store_dwordx4 v210, v[88:91], s[20:21] offset:2048 nt
	global_store_dwordx4 v210, v[92:95], s[20:21] offset:3072 nt
	s_add_u32 s18, s18, 0x400000
	s_addc_u32 s19, s19, 0
	s_add_u32 s20, s20, 0x400000
	s_addc_u32 s21, s21, 0
	s_branch .LBB0_454
.Lpost1_orig:
	v_lshlrev_b32_e32 v16, 2, v0
	v_and_b32_e32 v0, 64, v254
	v_add_u32_e32 v0, 64, v0
	v_xor_b32_e32 v1, 32, v254
	v_cmp_lt_i32_e32 vcc, v1, v0
	v_ashrrev_i32_e32 v17, 31, v16
	v_readlane_b32 s4, v255, 3
	v_cndmask_b32_e32 v1, v254, v1, vcc
	v_lshlrev_b32_e32 v46, 2, v1
	v_xor_b32_e32 v1, 16, v254
	v_cmp_lt_i32_e32 vcc, v1, v0
	v_lshlrev_b64 v[20:21], 2, v[16:17]
	v_readlane_b32 s14, v255, 13
	v_cndmask_b32_e32 v1, v254, v1, vcc
	v_lshlrev_b32_e32 v47, 2, v1
	v_xor_b32_e32 v1, 8, v254
	v_cmp_lt_i32_e32 vcc, v1, v0
	v_readlane_b32 s15, v255, 14
	s_mov_b64 s[2:3], 0x1000
	v_cndmask_b32_e32 v1, v254, v1, vcc
	v_lshlrev_b32_e32 v48, 2, v1
	v_xor_b32_e32 v1, 4, v254
	v_cmp_lt_i32_e32 vcc, v1, v0
	v_lshl_add_u64 v[2:3], s[14:15], 0, v[20:21]
	s_lshl_b32 s0, s33, 4
	v_cndmask_b32_e32 v1, v254, v1, vcc
	v_lshlrev_b32_e32 v49, 2, v1
	v_xor_b32_e32 v1, 2, v254
	v_lshl_add_u64 v[24:25], v[2:3], 0, s[2:3]
	s_ashr_i32 s27, s26, 31
	s_mul_i32 s2, s26, 0x3000
	v_cmp_lt_i32_e32 vcc, v1, v0
	s_mul_hi_i32 s1, s26, 0x3000
	s_add_u32 s2, s62, s2
	v_cndmask_b32_e32 v1, v254, v1, vcc
	v_readlane_b32 s5, v255, 4
	s_addc_u32 s3, s63, s1
	s_add_i32 s4, s26, s82
	v_lshlrev_b32_e32 v50, 2, v1
	v_xor_b32_e32 v1, 1, v254
	s_ashr_i32 s5, s4, 31
	v_cmp_lt_i32_e32 vcc, v1, v0
	s_ashr_i32 s1, s0, 31
	s_lshl_b64 s[4:5], s[4:5], 12
	v_cndmask_b32_e32 v0, v254, v1, vcc
	v_readlane_b32 s6, v255, 5
	v_readlane_b32 s7, v255, 6
	v_readlane_b32 s8, v255, 7
	v_readlane_b32 s9, v255, 8
	s_add_u32 s4, s30, s4
	v_lshlrev_b32_e32 v51, 2, v0
	v_lshlrev_b64 v[0:1], 1, v[16:17]
	s_addc_u32 s5, s31, s5
	s_lshl_b64 s[6:7], s[0:1], 12
	s_lshl_b64 s[8:9], s[26:27], 12
	v_lshl_add_u64 v[18:19], s[62:63], 0, v[0:1]
	v_readlane_b32 s10, v255, 9
	v_readlane_b32 s11, v255, 10
	v_readlane_b32 s16, v255, 15
	v_lshl_add_u64 v[0:1], s[2:3], 0, v[0:1]
	s_mov_b64 s[2:3], 0x400
	s_add_u32 s8, s30, s8
	v_lshl_add_u64 v[22:23], s[30:31], 0, v[20:21]
	v_lshl_add_u64 v[26:27], v[0:1], 0, s[2:3]
	s_mul_i32 s2, s33, 0x30000
	s_mul_hi_i32 s3, s0, 0x3000
	s_addc_u32 s9, s31, s9
	v_mov_b32_e32 v52, 0x3000
	s_mov_b64 s[10:11], 0xe000
	s_mov_b32 s1, 0xe000
	v_mov_b32_e32 v53, 0x358637bd
	s_mov_b32 s16, 0x800000
	v_readlane_b32 s12, v255, 11
	v_readlane_b32 s13, v255, 12
	v_readlane_b32 s17, v255, 16
	v_readlane_b32 s18, v255, 17
	v_readlane_b32 s19, v255, 18
	s_branch .LBB0_452
